# EpiRes epilogues L10/L12/L13 rewritten: loads hoisted, counted vmcnt
# speedup vs baseline: 1.0065x; 1.0065x over previous
; __device__ __forceinline__ u32x4 pack8(f32x4 a, f32x4 b) { u32x4 w; w.x = cvt_pk_bf16(a[0], a[1]); w.y = cvt_pk_bf16(a[2], a[3]); w.z = cvt_pk_bf16(b[0], b[1]); w.w = cvt_pk_bf16(b[2], b[3]); return w; }
; __device__ __forceinline__ void unpack8(u32x4 w, f32x4& a, f32x4& b) { a = (f32x4){bflo(w.x), bfhi(w.x), bflo(w.y), bfhi(w.y)}; b = (f32x4){bflo(w.z), bfhi(w.z), bflo(w.w), bfhi(w.w)}; }
; __device__ __forceinline__ float sigmoidf_(float x) { return __builtin_amdgcn_rcpf(1.f + __builtin_amdgcn_exp2f(-1.4426950408889634f * x)); }
; __device__ __forceinline__ float xhalf_sum(float v) { const auto r_ = __builtin_amdgcn_permlane32_swap(__float_as_uint(v), __float_as_uint(v), false, false); return __uint_as_float(r_[0]) + __uint_as_float(r_[1]); }
; #define EPI_ROWS_END if (m & 1) asm volatile("" ::: "memory"); }
;     __device__ __forceinline__ void operator()(AccRef acc, const Unit& u, int wr, int wc, int fr, int fq) const {
;         const int col0 = u.pn * 256 + wc * 32 + 8 * fq;
;         EPI_ROWS_BEGIN
;             float r = 1.f; if (MODE == 1) r = RSL(u, row);
;             float ss = 0.f;
; #pragma unroll
;             for (int bj = 0; bj < 2; ++bj) {
;                 const size_t off = (size_t)row * 1024 + col0 + bj * 128;
;                 f32x4 a0 = acc[ai][bj][m][0], a1 = acc[ai][bj][m][1];
;                 if (MODE == 1) { f32x4 t0, t1; unpack8(*(const u32x4*)(tp + off), t0, t1);
; #pragma unroll
;                     for (int e = 0; e < 4; ++e) { a0[e] = sigmoidf_(a0[e] * r) * t0[e]; a1[e] = sigmoidf_(a1[e] * r) * t1[e]; } }
;                 const f32x4 n0 = *(const f32x4*)(xold + off) + a0, n1 = *(const f32x4*)(xold + off + 4) + a1;
;                 *(f32x4*)(xf + off) = n0; *(f32x4*)(xf + off + 4) = n1;
;                 if (MODE == 0) *(u32x4*)(xb + off) = pack8(n0, n1);
;                 ss += (n0[0] * n0[0] + n0[1] * n0[1]) + (n0[2] * n0[2] + n0[3] * n0[3]) + (n1[0] * n1[0] + n1[1] * n1[1]) + (n1[2] * n1[2] + n1[3] * n1[3]);
;             }
;             ss += __shfl_xor(ss, 16); ss = xhalf_sum(ss);
;             if (fq == 0) ssq_out[(size_t)row * 16 + u.pn * 4 + wc] = ss;
;         EPI_ROWS_END
.LBB0_1466:
	s_waitcnt lgkmcnt(0)
	s_lshl_b32 s0, s36, 20
	s_lshl_b32 s1, s31, 10
	s_add_u32 s0, s0, s1
	v_lshlrev_b32_e32 v141, 12, v144
	v_lshl_add_u32 v141, v146, 2, v141
	v_add_u32_e32 v198, s0, v141
	v_add_u32_e32 v199, 0x10000, v198
	v_add_u32_e32 v216, 0x20000, v198
	v_add_u32_e32 v217, 0x30000, v198
	v_add_u32_e32 v218, 0x80000, v198
	v_add_u32_e32 v219, 0x90000, v198
	v_add_u32_e32 v220, 0xa0000, v198
	v_add_u32_e32 v221, 0xb0000, v198
	global_load_dwordx4 v[148:151], v198, s[16:17]
	global_load_dwordx4 v[152:155], v198, s[16:17] offset:16
	global_load_dwordx4 v[156:159], v198, s[16:17] offset:512
	global_load_dwordx4 v[160:163], v198, s[16:17] offset:528
	global_load_dwordx4 v[164:167], v199, s[16:17]
	global_load_dwordx4 v[168:171], v199, s[16:17] offset:16
	global_load_dwordx4 v[172:175], v199, s[16:17] offset:512
	global_load_dwordx4 v[176:179], v199, s[16:17] offset:528
	global_load_dwordx4 v[180:183], v216, s[16:17]
	global_load_dwordx4 v[184:187], v216, s[16:17] offset:16
	global_load_dwordx4 v[188:191], v216, s[16:17] offset:512
	global_load_dwordx4 v[192:195], v216, s[16:17] offset:528
	global_load_dwordx4 v[200:203], v217, s[16:17]
	global_load_dwordx4 v[204:207], v217, s[16:17] offset:16
	global_load_dwordx4 v[208:211], v217, s[16:17] offset:512
	global_load_dwordx4 v[212:215], v217, s[16:17] offset:528
	s_lshl_b32 s0, s36, 14
	s_lshl_b32 s1, s31, 4
	s_add_u32 s0, s0, s1
	s_lshl_b32 s1, s58, 2
	s_add_u32 s0, s0, s1
	v_lshl_add_u32 v236, v144, 6, s0
	v_xor_b32_e32 v140, 16, v226
	v_lshlrev_b32_e32 v140, 2, v140
	s_waitcnt vmcnt(12)
	v_pk_add_f32 v[122:123], v[122:123], v[148:149]
	v_pk_add_f32 v[124:125], v[124:125], v[150:151]
	v_pk_add_f32 v[126:127], v[126:127], v[152:153]
	v_pk_add_f32 v[128:129], v[128:129], v[154:155]
	v_pk_add_f32 v[118:119], v[118:119], v[156:157]
	v_pk_add_f32 v[120:121], v[120:121], v[158:159]
	v_pk_add_f32 v[114:115], v[114:115], v[160:161]
	v_pk_add_f32 v[116:117], v[116:117], v[162:163]
	global_store_dwordx4 v198, v[122:125], s[18:19]
	global_store_dwordx4 v198, v[126:129], s[18:19] offset:16
	global_store_dwordx4 v198, v[118:121], s[18:19] offset:512
	global_store_dwordx4 v198, v[114:117], s[18:19] offset:528
	v_cvt_pk_bf16_f32 v148, v122, v123
	v_cvt_pk_bf16_f32 v149, v124, v125
	v_cvt_pk_bf16_f32 v150, v126, v127
	v_cvt_pk_bf16_f32 v151, v128, v129
	v_cvt_pk_bf16_f32 v152, v118, v119
	v_cvt_pk_bf16_f32 v153, v120, v121
	v_cvt_pk_bf16_f32 v154, v114, v115
	v_cvt_pk_bf16_f32 v155, v116, v117
	v_lshrrev_b32_e32 v141, 1, v198
	global_store_dwordx4 v141, v[148:151], s[22:23]
	global_store_dwordx4 v141, v[152:155], s[22:23] offset:256
	v_mul_f32_e32 v142, v123, v123
	v_fmac_f32_e32 v142, v122, v122
	v_mul_f32_e32 v143, v125, v125
	v_fmac_f32_e32 v143, v124, v124
	v_add_f32_e32 v143, v142, v143
	v_mul_f32_e32 v142, v127, v127
	v_fmac_f32_e32 v142, v126, v126
	v_add_f32_e32 v143, v143, v142
	v_mul_f32_e32 v142, v129, v129
	v_fmac_f32_e32 v142, v128, v128
	v_add_f32_e32 v237, v142, v143
	v_mul_f32_e32 v142, v119, v119
	v_fmac_f32_e32 v142, v118, v118
	v_mul_f32_e32 v143, v121, v121
	v_fmac_f32_e32 v143, v120, v120
	v_add_f32_e32 v143, v142, v143
	v_mul_f32_e32 v142, v115, v115
	v_fmac_f32_e32 v142, v114, v114
	v_add_f32_e32 v143, v143, v142
	v_mul_f32_e32 v142, v117, v117
	v_fmac_f32_e32 v142, v116, v116
	v_add_f32_e32 v143, v142, v143
	v_add_f32_e32 v122, v237, v143
	ds_bpermute_b32 v123, v140, v122
	global_load_dwordx4 v[148:151], v218, s[16:17]
	global_load_dwordx4 v[152:155], v218, s[16:17] offset:16
	global_load_dwordx4 v[156:159], v218, s[16:17] offset:512
	global_load_dwordx4 v[160:163], v218, s[16:17] offset:528
	s_waitcnt vmcnt(18)
	v_pk_add_f32 v[110:111], v[110:111], v[164:165]
	v_pk_add_f32 v[112:113], v[112:113], v[166:167]
	v_pk_add_f32 v[106:107], v[106:107], v[168:169]
	v_pk_add_f32 v[108:109], v[108:109], v[170:171]
	v_pk_add_f32 v[102:103], v[102:103], v[172:173]
	v_pk_add_f32 v[104:105], v[104:105], v[174:175]
	v_pk_add_f32 v[98:99], v[98:99], v[176:177]
	v_pk_add_f32 v[100:101], v[100:101], v[178:179]
	global_store_dwordx4 v199, v[110:113], s[18:19]
	global_store_dwordx4 v199, v[106:109], s[18:19] offset:16
	global_store_dwordx4 v199, v[102:105], s[18:19] offset:512
	global_store_dwordx4 v199, v[98:101], s[18:19] offset:528
	v_cvt_pk_bf16_f32 v164, v110, v111
	v_cvt_pk_bf16_f32 v165, v112, v113
	v_cvt_pk_bf16_f32 v166, v106, v107
	v_cvt_pk_bf16_f32 v167, v108, v109
	v_cvt_pk_bf16_f32 v168, v102, v103
	v_cvt_pk_bf16_f32 v169, v104, v105
	v_cvt_pk_bf16_f32 v170, v98, v99
	v_cvt_pk_bf16_f32 v171, v100, v101
	v_lshrrev_b32_e32 v141, 1, v199
	global_store_dwordx4 v141, v[164:167], s[22:23]
	global_store_dwordx4 v141, v[168:171], s[22:23] offset:256
	v_mul_f32_e32 v142, v111, v111
	v_fmac_f32_e32 v142, v110, v110
	v_mul_f32_e32 v143, v113, v113
	v_fmac_f32_e32 v143, v112, v112
	v_add_f32_e32 v143, v142, v143
	v_mul_f32_e32 v142, v107, v107
	v_fmac_f32_e32 v142, v106, v106
	v_add_f32_e32 v143, v143, v142
	v_mul_f32_e32 v142, v109, v109
	v_fmac_f32_e32 v142, v108, v108
	v_add_f32_e32 v237, v142, v143
	v_mul_f32_e32 v142, v103, v103
	v_fmac_f32_e32 v142, v102, v102
	v_mul_f32_e32 v143, v105, v105
	v_fmac_f32_e32 v143, v104, v104
	v_add_f32_e32 v143, v142, v143
	v_mul_f32_e32 v142, v99, v99
	v_fmac_f32_e32 v142, v98, v98
	v_add_f32_e32 v143, v143, v142
	v_mul_f32_e32 v142, v101, v101
	v_fmac_f32_e32 v142, v100, v100
	v_add_f32_e32 v143, v142, v143
	v_add_f32_e32 v110, v237, v143
	ds_bpermute_b32 v111, v140, v110
	global_load_dwordx4 v[164:167], v219, s[16:17]
	global_load_dwordx4 v[168:171], v219, s[16:17] offset:16
	global_load_dwordx4 v[172:175], v219, s[16:17] offset:512
	global_load_dwordx4 v[176:179], v219, s[16:17] offset:528
	s_waitcnt vmcnt(24)
; __device__ __forceinline__ u32x4 pack8(f32x4 a, f32x4 b) { u32x4 w; w.x = cvt_pk_bf16(a[0], a[1]); w.y = cvt_pk_bf16(a[2], a[3]); w.z = cvt_pk_bf16(b[0], b[1]); w.w = cvt_pk_bf16(b[2], b[3]); return w; }
; __device__ __forceinline__ void unpack8(u32x4 w, f32x4& a, f32x4& b) { a = (f32x4){bflo(w.x), bfhi(w.x), bflo(w.y), bfhi(w.y)}; b = (f32x4){bflo(w.z), bfhi(w.z), bflo(w.w), bfhi(w.w)}; }
; __device__ __forceinline__ float sigmoidf_(float x) { return __builtin_amdgcn_rcpf(1.f + __builtin_amdgcn_exp2f(-1.4426950408889634f * x)); }
; __device__ __forceinline__ float xhalf_sum(float v) { const auto r_ = __builtin_amdgcn_permlane32_swap(__float_as_uint(v), __float_as_uint(v), false, false); return __uint_as_float(r_[0]) + __uint_as_float(r_[1]); }
; #define EPI_ROWS_END if (m & 1) asm volatile("" ::: "memory"); }
;     __device__ __forceinline__ void operator()(AccRef acc, const Unit& u, int wr, int wc, int fr, int fq) const {
;         const int col0 = u.pn * 256 + wc * 32 + 8 * fq;
;         EPI_ROWS_BEGIN
;             float r = 1.f; if (MODE == 1) r = RSL(u, row);
;             float ss = 0.f;
; #pragma unroll
;             for (int bj = 0; bj < 2; ++bj) {
;                 const size_t off = (size_t)row * 1024 + col0 + bj * 128;
;                 f32x4 a0 = acc[ai][bj][m][0], a1 = acc[ai][bj][m][1];
;                 if (MODE == 1) { f32x4 t0, t1; unpack8(*(const u32x4*)(tp + off), t0, t1);
; #pragma unroll
;                     for (int e = 0; e < 4; ++e) { a0[e] = sigmoidf_(a0[e] * r) * t0[e]; a1[e] = sigmoidf_(a1[e] * r) * t1[e]; } }
;                 const f32x4 n0 = *(const f32x4*)(xold + off) + a0, n1 = *(const f32x4*)(xold + off + 4) + a1;
;                 *(f32x4*)(xf + off) = n0; *(f32x4*)(xf + off + 4) = n1;
;                 if (MODE == 0) *(u32x4*)(xb + off) = pack8(n0, n1);
;                 ss += (n0[0] * n0[0] + n0[1] * n0[1]) + (n0[2] * n0[2] + n0[3] * n0[3]) + (n1[0] * n1[0] + n1[1] * n1[1]) + (n1[2] * n1[2] + n1[3] * n1[3]);
;             }
;             ss += __shfl_xor(ss, 16); ss = xhalf_sum(ss);
;             if (fq == 0) ssq_out[(size_t)row * 16 + u.pn * 4 + wc] = ss;
;         EPI_ROWS_END
	v_pk_add_f32 v[94:95], v[94:95], v[180:181]
	v_pk_add_f32 v[96:97], v[96:97], v[182:183]
	v_pk_add_f32 v[90:91], v[90:91], v[184:185]
	v_pk_add_f32 v[92:93], v[92:93], v[186:187]
	v_pk_add_f32 v[86:87], v[86:87], v[188:189]
	v_pk_add_f32 v[88:89], v[88:89], v[190:191]
	v_pk_add_f32 v[82:83], v[82:83], v[192:193]
	v_pk_add_f32 v[84:85], v[84:85], v[194:195]
	global_store_dwordx4 v216, v[94:97], s[18:19]
	global_store_dwordx4 v216, v[90:93], s[18:19] offset:16
	global_store_dwordx4 v216, v[86:89], s[18:19] offset:512
	global_store_dwordx4 v216, v[82:85], s[18:19] offset:528
	v_cvt_pk_bf16_f32 v180, v94, v95
	v_cvt_pk_bf16_f32 v181, v96, v97
	v_cvt_pk_bf16_f32 v182, v90, v91
	v_cvt_pk_bf16_f32 v183, v92, v93
	v_cvt_pk_bf16_f32 v184, v86, v87
	v_cvt_pk_bf16_f32 v185, v88, v89
	v_cvt_pk_bf16_f32 v186, v82, v83
	v_cvt_pk_bf16_f32 v187, v84, v85
	v_lshrrev_b32_e32 v141, 1, v216
	global_store_dwordx4 v141, v[180:183], s[22:23]
	global_store_dwordx4 v141, v[184:187], s[22:23] offset:256
	v_mul_f32_e32 v142, v95, v95
	v_fmac_f32_e32 v142, v94, v94
	v_mul_f32_e32 v143, v97, v97
	v_fmac_f32_e32 v143, v96, v96
	v_add_f32_e32 v143, v142, v143
	v_mul_f32_e32 v142, v91, v91
	v_fmac_f32_e32 v142, v90, v90
	v_add_f32_e32 v143, v143, v142
	v_mul_f32_e32 v142, v93, v93
	v_fmac_f32_e32 v142, v92, v92
	v_add_f32_e32 v237, v142, v143
	v_mul_f32_e32 v142, v87, v87
	v_fmac_f32_e32 v142, v86, v86
	v_mul_f32_e32 v143, v89, v89
	v_fmac_f32_e32 v143, v88, v88
	v_add_f32_e32 v143, v142, v143
	v_mul_f32_e32 v142, v83, v83
	v_fmac_f32_e32 v142, v82, v82
	v_add_f32_e32 v143, v143, v142
	v_mul_f32_e32 v142, v85, v85
	v_fmac_f32_e32 v142, v84, v84
	v_add_f32_e32 v143, v142, v143
	v_add_f32_e32 v94, v237, v143
	ds_bpermute_b32 v95, v140, v94
	global_load_dwordx4 v[180:183], v220, s[16:17]
	global_load_dwordx4 v[184:187], v220, s[16:17] offset:16
	global_load_dwordx4 v[188:191], v220, s[16:17] offset:512
	global_load_dwordx4 v[192:195], v220, s[16:17] offset:528
	s_waitcnt vmcnt(30)
	v_pk_add_f32 v[78:79], v[78:79], v[200:201]
	v_pk_add_f32 v[80:81], v[80:81], v[202:203]
	v_pk_add_f32 v[74:75], v[74:75], v[204:205]
	v_pk_add_f32 v[76:77], v[76:77], v[206:207]
	v_pk_add_f32 v[70:71], v[70:71], v[208:209]
	v_pk_add_f32 v[72:73], v[72:73], v[210:211]
	v_pk_add_f32 v[66:67], v[66:67], v[212:213]
	v_pk_add_f32 v[68:69], v[68:69], v[214:215]
	global_store_dwordx4 v217, v[78:81], s[18:19]
	global_store_dwordx4 v217, v[74:77], s[18:19] offset:16
	global_store_dwordx4 v217, v[70:73], s[18:19] offset:512
	global_store_dwordx4 v217, v[66:69], s[18:19] offset:528
	v_cvt_pk_bf16_f32 v200, v78, v79
	v_cvt_pk_bf16_f32 v201, v80, v81
	v_cvt_pk_bf16_f32 v202, v74, v75
	v_cvt_pk_bf16_f32 v203, v76, v77
	v_cvt_pk_bf16_f32 v204, v70, v71
	v_cvt_pk_bf16_f32 v205, v72, v73
	v_cvt_pk_bf16_f32 v206, v66, v67
	v_cvt_pk_bf16_f32 v207, v68, v69
	v_lshrrev_b32_e32 v141, 1, v217
	global_store_dwordx4 v141, v[200:203], s[22:23]
	global_store_dwordx4 v141, v[204:207], s[22:23] offset:256
	v_mul_f32_e32 v142, v79, v79
	v_fmac_f32_e32 v142, v78, v78
	v_mul_f32_e32 v143, v81, v81
	v_fmac_f32_e32 v143, v80, v80
	v_add_f32_e32 v143, v142, v143
	v_mul_f32_e32 v142, v75, v75
	v_fmac_f32_e32 v142, v74, v74
	v_add_f32_e32 v143, v143, v142
	v_mul_f32_e32 v142, v77, v77
	v_fmac_f32_e32 v142, v76, v76
	v_add_f32_e32 v237, v142, v143
	v_mul_f32_e32 v142, v71, v71
	v_fmac_f32_e32 v142, v70, v70
	v_mul_f32_e32 v143, v73, v73
	v_fmac_f32_e32 v143, v72, v72
	v_add_f32_e32 v143, v142, v143
	v_mul_f32_e32 v142, v67, v67
	v_fmac_f32_e32 v142, v66, v66
	v_add_f32_e32 v143, v143, v142
	v_mul_f32_e32 v142, v69, v69
	v_fmac_f32_e32 v142, v68, v68
	v_add_f32_e32 v143, v142, v143
	v_add_f32_e32 v78, v237, v143
	ds_bpermute_b32 v79, v140, v78
	global_load_dwordx4 v[200:203], v221, s[16:17]
	global_load_dwordx4 v[204:207], v221, s[16:17] offset:16
	global_load_dwordx4 v[208:211], v221, s[16:17] offset:512
	global_load_dwordx4 v[212:215], v221, s[16:17] offset:528
	s_waitcnt vmcnt(30)
	v_pk_add_f32 v[62:63], v[62:63], v[148:149]
	v_pk_add_f32 v[64:65], v[64:65], v[150:151]
	v_pk_add_f32 v[58:59], v[58:59], v[152:153]
	v_pk_add_f32 v[60:61], v[60:61], v[154:155]
	v_pk_add_f32 v[54:55], v[54:55], v[156:157]
	v_pk_add_f32 v[56:57], v[56:57], v[158:159]
	v_pk_add_f32 v[50:51], v[50:51], v[160:161]
	v_pk_add_f32 v[52:53], v[52:53], v[162:163]
	global_store_dwordx4 v218, v[62:65], s[18:19]
	global_store_dwordx4 v218, v[58:61], s[18:19] offset:16
	global_store_dwordx4 v218, v[54:57], s[18:19] offset:512
	global_store_dwordx4 v218, v[50:53], s[18:19] offset:528
	v_cvt_pk_bf16_f32 v148, v62, v63
	v_cvt_pk_bf16_f32 v149, v64, v65
	v_cvt_pk_bf16_f32 v150, v58, v59
	v_cvt_pk_bf16_f32 v151, v60, v61
	v_cvt_pk_bf16_f32 v152, v54, v55
	v_cvt_pk_bf16_f32 v153, v56, v57
	v_cvt_pk_bf16_f32 v154, v50, v51
	v_cvt_pk_bf16_f32 v155, v52, v53
	v_lshrrev_b32_e32 v141, 1, v218
	global_store_dwordx4 v141, v[148:151], s[22:23]
	global_store_dwordx4 v141, v[152:155], s[22:23] offset:256
	v_mul_f32_e32 v142, v63, v63
	v_fmac_f32_e32 v142, v62, v62
	v_mul_f32_e32 v143, v65, v65
	v_fmac_f32_e32 v143, v64, v64
	v_add_f32_e32 v143, v142, v143
	v_mul_f32_e32 v142, v59, v59
	v_fmac_f32_e32 v142, v58, v58
	v_add_f32_e32 v143, v143, v142
	v_mul_f32_e32 v142, v61, v61
	v_fmac_f32_e32 v142, v60, v60
	v_add_f32_e32 v237, v142, v143
	v_mul_f32_e32 v142, v55, v55
	v_fmac_f32_e32 v142, v54, v54
	v_mul_f32_e32 v143, v57, v57
	v_fmac_f32_e32 v143, v56, v56
	v_add_f32_e32 v143, v142, v143
	v_mul_f32_e32 v142, v51, v51
	v_fmac_f32_e32 v142, v50, v50
	v_add_f32_e32 v143, v143, v142
	v_mul_f32_e32 v142, v53, v53
	v_fmac_f32_e32 v142, v52, v52
	v_add_f32_e32 v143, v142, v143
	v_add_f32_e32 v62, v237, v143
	ds_bpermute_b32 v63, v140, v62
	s_waitcnt vmcnt(26)
; __device__ __forceinline__ u32x4 pack8(f32x4 a, f32x4 b) { u32x4 w; w.x = cvt_pk_bf16(a[0], a[1]); w.y = cvt_pk_bf16(a[2], a[3]); w.z = cvt_pk_bf16(b[0], b[1]); w.w = cvt_pk_bf16(b[2], b[3]); return w; }
; __device__ __forceinline__ void unpack8(u32x4 w, f32x4& a, f32x4& b) { a = (f32x4){bflo(w.x), bfhi(w.x), bflo(w.y), bfhi(w.y)}; b = (f32x4){bflo(w.z), bfhi(w.z), bflo(w.w), bfhi(w.w)}; }
; __device__ __forceinline__ float sigmoidf_(float x) { return __builtin_amdgcn_rcpf(1.f + __builtin_amdgcn_exp2f(-1.4426950408889634f * x)); }
; __device__ __forceinline__ float xhalf_sum(float v) { const auto r_ = __builtin_amdgcn_permlane32_swap(__float_as_uint(v), __float_as_uint(v), false, false); return __uint_as_float(r_[0]) + __uint_as_float(r_[1]); }
; #define EPI_ROWS_END if (m & 1) asm volatile("" ::: "memory"); }
;     __device__ __forceinline__ void operator()(AccRef acc, const Unit& u, int wr, int wc, int fr, int fq) const {
;         const int col0 = u.pn * 256 + wc * 32 + 8 * fq;
;         EPI_ROWS_BEGIN
;             float r = 1.f; if (MODE == 1) r = RSL(u, row);
;             float ss = 0.f;
; #pragma unroll
;             for (int bj = 0; bj < 2; ++bj) {
;                 const size_t off = (size_t)row * 1024 + col0 + bj * 128;
;                 f32x4 a0 = acc[ai][bj][m][0], a1 = acc[ai][bj][m][1];
;                 if (MODE == 1) { f32x4 t0, t1; unpack8(*(const u32x4*)(tp + off), t0, t1);
; #pragma unroll
;                     for (int e = 0; e < 4; ++e) { a0[e] = sigmoidf_(a0[e] * r) * t0[e]; a1[e] = sigmoidf_(a1[e] * r) * t1[e]; } }
;                 const f32x4 n0 = *(const f32x4*)(xold + off) + a0, n1 = *(const f32x4*)(xold + off + 4) + a1;
;                 *(f32x4*)(xf + off) = n0; *(f32x4*)(xf + off + 4) = n1;
;                 if (MODE == 0) *(u32x4*)(xb + off) = pack8(n0, n1);
;                 ss += (n0[0] * n0[0] + n0[1] * n0[1]) + (n0[2] * n0[2] + n0[3] * n0[3]) + (n1[0] * n1[0] + n1[1] * n1[1]) + (n1[2] * n1[2] + n1[3] * n1[3]);
;             }
;             ss += __shfl_xor(ss, 16); ss = xhalf_sum(ss);
;             if (fq == 0) ssq_out[(size_t)row * 16 + u.pn * 4 + wc] = ss;
;         EPI_ROWS_END
	v_pk_add_f32 v[46:47], v[46:47], v[164:165]
	v_pk_add_f32 v[48:49], v[48:49], v[166:167]
	v_pk_add_f32 v[42:43], v[42:43], v[168:169]
	v_pk_add_f32 v[44:45], v[44:45], v[170:171]
	v_pk_add_f32 v[38:39], v[38:39], v[172:173]
	v_pk_add_f32 v[40:41], v[40:41], v[174:175]
	v_pk_add_f32 v[34:35], v[34:35], v[176:177]
	v_pk_add_f32 v[36:37], v[36:37], v[178:179]
	global_store_dwordx4 v219, v[46:49], s[18:19]
	global_store_dwordx4 v219, v[42:45], s[18:19] offset:16
	global_store_dwordx4 v219, v[38:41], s[18:19] offset:512
	global_store_dwordx4 v219, v[34:37], s[18:19] offset:528
	v_cvt_pk_bf16_f32 v164, v46, v47
	v_cvt_pk_bf16_f32 v165, v48, v49
	v_cvt_pk_bf16_f32 v166, v42, v43
	v_cvt_pk_bf16_f32 v167, v44, v45
	v_cvt_pk_bf16_f32 v168, v38, v39
	v_cvt_pk_bf16_f32 v169, v40, v41
	v_cvt_pk_bf16_f32 v170, v34, v35
	v_cvt_pk_bf16_f32 v171, v36, v37
	v_lshrrev_b32_e32 v141, 1, v219
	global_store_dwordx4 v141, v[164:167], s[22:23]
	global_store_dwordx4 v141, v[168:171], s[22:23] offset:256
	v_mul_f32_e32 v142, v47, v47
	v_fmac_f32_e32 v142, v46, v46
	v_mul_f32_e32 v143, v49, v49
	v_fmac_f32_e32 v143, v48, v48
	v_add_f32_e32 v143, v142, v143
	v_mul_f32_e32 v142, v43, v43
	v_fmac_f32_e32 v142, v42, v42
	v_add_f32_e32 v143, v143, v142
	v_mul_f32_e32 v142, v45, v45
	v_fmac_f32_e32 v142, v44, v44
	v_add_f32_e32 v237, v142, v143
	v_mul_f32_e32 v142, v39, v39
	v_fmac_f32_e32 v142, v38, v38
	v_mul_f32_e32 v143, v41, v41
	v_fmac_f32_e32 v143, v40, v40
	v_add_f32_e32 v143, v142, v143
	v_mul_f32_e32 v142, v35, v35
	v_fmac_f32_e32 v142, v34, v34
	v_add_f32_e32 v143, v143, v142
	v_mul_f32_e32 v142, v37, v37
	v_fmac_f32_e32 v142, v36, v36
	v_add_f32_e32 v143, v142, v143
	v_add_f32_e32 v46, v237, v143
	ds_bpermute_b32 v47, v140, v46
	s_waitcnt vmcnt(22)
	v_pk_add_f32 v[30:31], v[30:31], v[180:181]
	v_pk_add_f32 v[32:33], v[32:33], v[182:183]
	v_pk_add_f32 v[26:27], v[26:27], v[184:185]
	v_pk_add_f32 v[28:29], v[28:29], v[186:187]
	v_pk_add_f32 v[22:23], v[22:23], v[188:189]
	v_pk_add_f32 v[24:25], v[24:25], v[190:191]
	v_pk_add_f32 v[18:19], v[18:19], v[192:193]
	v_pk_add_f32 v[20:21], v[20:21], v[194:195]
	global_store_dwordx4 v220, v[30:33], s[18:19]
	global_store_dwordx4 v220, v[26:29], s[18:19] offset:16
	global_store_dwordx4 v220, v[22:25], s[18:19] offset:512
	global_store_dwordx4 v220, v[18:21], s[18:19] offset:528
	v_cvt_pk_bf16_f32 v180, v30, v31
	v_cvt_pk_bf16_f32 v181, v32, v33
	v_cvt_pk_bf16_f32 v182, v26, v27
	v_cvt_pk_bf16_f32 v183, v28, v29
	v_cvt_pk_bf16_f32 v184, v22, v23
	v_cvt_pk_bf16_f32 v185, v24, v25
	v_cvt_pk_bf16_f32 v186, v18, v19
	v_cvt_pk_bf16_f32 v187, v20, v21
	v_lshrrev_b32_e32 v141, 1, v220
	global_store_dwordx4 v141, v[180:183], s[22:23]
	global_store_dwordx4 v141, v[184:187], s[22:23] offset:256
	v_mul_f32_e32 v142, v31, v31
	v_fmac_f32_e32 v142, v30, v30
	v_mul_f32_e32 v143, v33, v33
	v_fmac_f32_e32 v143, v32, v32
	v_add_f32_e32 v143, v142, v143
	v_mul_f32_e32 v142, v27, v27
	v_fmac_f32_e32 v142, v26, v26
	v_add_f32_e32 v143, v143, v142
	v_mul_f32_e32 v142, v29, v29
	v_fmac_f32_e32 v142, v28, v28
	v_add_f32_e32 v237, v142, v143
	v_mul_f32_e32 v142, v23, v23
	v_fmac_f32_e32 v142, v22, v22
	v_mul_f32_e32 v143, v25, v25
	v_fmac_f32_e32 v143, v24, v24
	v_add_f32_e32 v143, v142, v143
	v_mul_f32_e32 v142, v19, v19
	v_fmac_f32_e32 v142, v18, v18
	v_add_f32_e32 v143, v143, v142
	v_mul_f32_e32 v142, v21, v21
	v_fmac_f32_e32 v142, v20, v20
	v_add_f32_e32 v143, v142, v143
	v_add_f32_e32 v30, v237, v143
	ds_bpermute_b32 v31, v140, v30
	s_waitcnt vmcnt(18)
	v_pk_add_f32 v[14:15], v[14:15], v[200:201]
	v_pk_add_f32 v[16:17], v[16:17], v[202:203]
	v_pk_add_f32 v[10:11], v[10:11], v[204:205]
	v_pk_add_f32 v[12:13], v[12:13], v[206:207]
	v_pk_add_f32 v[6:7], v[6:7], v[208:209]
	v_pk_add_f32 v[8:9], v[8:9], v[210:211]
	v_pk_add_f32 v[2:3], v[2:3], v[212:213]
	v_pk_add_f32 v[4:5], v[4:5], v[214:215]
	global_store_dwordx4 v221, v[14:17], s[18:19]
	global_store_dwordx4 v221, v[10:13], s[18:19] offset:16
	global_store_dwordx4 v221, v[6:9], s[18:19] offset:512
	global_store_dwordx4 v221, v[2:5], s[18:19] offset:528
	v_cvt_pk_bf16_f32 v200, v14, v15
	v_cvt_pk_bf16_f32 v201, v16, v17
	v_cvt_pk_bf16_f32 v202, v10, v11
	v_cvt_pk_bf16_f32 v203, v12, v13
	v_cvt_pk_bf16_f32 v204, v6, v7
	v_cvt_pk_bf16_f32 v205, v8, v9
	v_cvt_pk_bf16_f32 v206, v2, v3
	v_cvt_pk_bf16_f32 v207, v4, v5
	v_lshrrev_b32_e32 v141, 1, v221
	global_store_dwordx4 v141, v[200:203], s[22:23]
	global_store_dwordx4 v141, v[204:207], s[22:23] offset:256
	v_mul_f32_e32 v142, v15, v15
	v_fmac_f32_e32 v142, v14, v14
	v_mul_f32_e32 v143, v17, v17
	v_fmac_f32_e32 v143, v16, v16
	v_add_f32_e32 v143, v142, v143
	v_mul_f32_e32 v142, v11, v11
	v_fmac_f32_e32 v142, v10, v10
	v_add_f32_e32 v143, v143, v142
	v_mul_f32_e32 v142, v13, v13
	v_fmac_f32_e32 v142, v12, v12
	v_add_f32_e32 v237, v142, v143
	v_mul_f32_e32 v142, v7, v7
	v_fmac_f32_e32 v142, v6, v6
	v_mul_f32_e32 v143, v9, v9
	v_fmac_f32_e32 v143, v8, v8
	v_add_f32_e32 v143, v142, v143
	v_mul_f32_e32 v142, v3, v3
	v_fmac_f32_e32 v142, v2, v2
	v_add_f32_e32 v143, v143, v142
	v_mul_f32_e32 v142, v5, v5
	v_fmac_f32_e32 v142, v4, v4
	v_add_f32_e32 v143, v142, v143
	v_add_f32_e32 v14, v237, v143
	ds_bpermute_b32 v15, v140, v14
	s_waitcnt lgkmcnt(0)
	v_add_f32_e32 v122, v122, v123
	v_add_f32_e32 v110, v110, v111
	v_add_f32_e32 v94, v94, v95
	v_add_f32_e32 v78, v78, v79
	v_add_f32_e32 v62, v62, v63
	v_add_f32_e32 v46, v46, v47
	v_add_f32_e32 v30, v30, v31
	v_add_f32_e32 v14, v14, v15
	v_mov_b32_e32 v123, v122
	v_mov_b32_e32 v111, v110
	v_mov_b32_e32 v95, v94
	v_mov_b32_e32 v79, v78
	v_mov_b32_e32 v63, v62
	v_mov_b32_e32 v47, v46
	v_mov_b32_e32 v31, v30
	v_mov_b32_e32 v15, v14
	s_nop 1
	v_permlane32_swap_b32_e32 v122, v123
	v_permlane32_swap_b32_e32 v110, v111
	v_permlane32_swap_b32_e32 v94, v95
	v_permlane32_swap_b32_e32 v78, v79
	v_permlane32_swap_b32_e32 v62, v63
	v_permlane32_swap_b32_e32 v46, v47
	v_permlane32_swap_b32_e32 v30, v31
	v_permlane32_swap_b32_e32 v14, v15
	v_add_f32_e32 v122, v122, v123
	v_add_f32_e32 v110, v110, v111
	v_add_f32_e32 v94, v94, v95
	v_add_f32_e32 v78, v78, v79
	v_add_f32_e32 v62, v62, v63
	v_add_f32_e32 v46, v46, v47
	v_add_f32_e32 v30, v30, v31
	v_add_f32_e32 v14, v14, v15
	s_and_saveexec_b64 s[38:39], s[44:45]
	global_store_dword v236, v122, s[24:25]
	v_add_u32_e32 v141, 0x400, v236
	global_store_dword v141, v110, s[24:25]
	v_add_u32_e32 v141, 0x800, v236
	global_store_dword v141, v94, s[24:25]
	v_add_u32_e32 v141, 0xc00, v236
	global_store_dword v141, v78, s[24:25]
	v_add_u32_e32 v141, 0x2000, v236
	global_store_dword v141, v62, s[24:25]
	v_add_u32_e32 v141, 0x2400, v236
	global_store_dword v141, v46, s[24:25]
	v_add_u32_e32 v141, 0x2800, v236
	global_store_dword v141, v30, s[24:25]
	v_add_u32_e32 v141, 0x2c00, v236
	global_store_dword v141, v14, s[24:25]
	s_or_b64 exec, exec, s[38:39]
	s_and_b64 vcc, exec, s[46:47]
	s_mov_b64 s[0:1], -1
	s_cbranch_vccnz .LBB0_1450
	s_andn2_b64 vcc, exec, s[20:21]
	s_cbranch_vccnz .LBB0_1449
	s_barrier
	s_branch .LBB0_1449

; __device__ __forceinline__ u32x4 pack8(f32x4 a, f32x4 b) { u32x4 w; w.x = cvt_pk_bf16(a[0], a[1]); w.y = cvt_pk_bf16(a[2], a[3]); w.z = cvt_pk_bf16(b[0], b[1]); w.w = cvt_pk_bf16(b[2], b[3]); return w; }
; __device__ __forceinline__ void unpack8(u32x4 w, f32x4& a, f32x4& b) { a = (f32x4){bflo(w.x), bfhi(w.x), bflo(w.y), bfhi(w.y)}; b = (f32x4){bflo(w.z), bfhi(w.z), bflo(w.w), bfhi(w.w)}; }
; __device__ __forceinline__ float sigmoidf_(float x) { return __builtin_amdgcn_rcpf(1.f + __builtin_amdgcn_exp2f(-1.4426950408889634f * x)); }
; __device__ __forceinline__ float xhalf_sum(float v) { const auto r_ = __builtin_amdgcn_permlane32_swap(__float_as_uint(v), __float_as_uint(v), false, false); return __uint_as_float(r_[0]) + __uint_as_float(r_[1]); }
; #define EPI_ROWS_END if (m & 1) asm volatile("" ::: "memory"); }
;     __device__ __forceinline__ void operator()(AccRef acc, const Unit& u, int wr, int wc, int fr, int fq) const {
;         const int col0 = u.pn * 256 + wc * 32 + 8 * fq;
;         EPI_ROWS_BEGIN
;             float r = 1.f; if (MODE == 1) r = RSL(u, row);
;             float ss = 0.f;
; #pragma unroll
;             for (int bj = 0; bj < 2; ++bj) {
;                 const size_t off = (size_t)row * 1024 + col0 + bj * 128;
;                 f32x4 a0 = acc[ai][bj][m][0], a1 = acc[ai][bj][m][1];
;                 if (MODE == 1) { f32x4 t0, t1; unpack8(*(const u32x4*)(tp + off), t0, t1);
; #pragma unroll
;                     for (int e = 0; e < 4; ++e) { a0[e] = sigmoidf_(a0[e] * r) * t0[e]; a1[e] = sigmoidf_(a1[e] * r) * t1[e]; } }
;                 const f32x4 n0 = *(const f32x4*)(xold + off) + a0, n1 = *(const f32x4*)(xold + off + 4) + a1;
;                 *(f32x4*)(xf + off) = n0; *(f32x4*)(xf + off + 4) = n1;
;                 if (MODE == 0) *(u32x4*)(xb + off) = pack8(n0, n1);
;                 ss += (n0[0] * n0[0] + n0[1] * n0[1]) + (n0[2] * n0[2] + n0[3] * n0[3]) + (n1[0] * n1[0] + n1[1] * n1[1]) + (n1[2] * n1[2] + n1[3] * n1[3]);
;             }
;             ss += __shfl_xor(ss, 16); ss = xhalf_sum(ss);
;             if (fq == 0) ssq_out[(size_t)row * 16 + u.pn * 4 + wc] = ss;
;         EPI_ROWS_END
.LBB0_1648:
	s_waitcnt lgkmcnt(0)
	s_lshl_b32 s40, s36, 20
	s_lshl_b32 s41, s31, 10
	s_add_u32 s40, s40, s41
	v_lshlrev_b32_e32 v141, 12, v144
	v_lshl_add_u32 v141, v146, 2, v141
	v_add_u32_e32 v198, s40, v141
	v_add_u32_e32 v199, 0x10000, v198
	v_add_u32_e32 v216, 0x20000, v198
	v_add_u32_e32 v217, 0x30000, v198
	v_add_u32_e32 v218, 0x80000, v198
	v_add_u32_e32 v219, 0x90000, v198
	v_add_u32_e32 v220, 0xa0000, v198
	v_add_u32_e32 v221, 0xb0000, v198
	global_load_dwordx4 v[148:151], v198, s[18:19]
	global_load_dwordx4 v[152:155], v198, s[18:19] offset:16
	global_load_dwordx4 v[156:159], v198, s[18:19] offset:512
	global_load_dwordx4 v[160:163], v198, s[18:19] offset:528
	global_load_dwordx4 v[164:167], v199, s[18:19]
	global_load_dwordx4 v[168:171], v199, s[18:19] offset:16
	global_load_dwordx4 v[172:175], v199, s[18:19] offset:512
	global_load_dwordx4 v[176:179], v199, s[18:19] offset:528
	global_load_dwordx4 v[180:183], v216, s[18:19]
	global_load_dwordx4 v[184:187], v216, s[18:19] offset:16
	global_load_dwordx4 v[188:191], v216, s[18:19] offset:512
	global_load_dwordx4 v[192:195], v216, s[18:19] offset:528
	global_load_dwordx4 v[200:203], v217, s[18:19]
	global_load_dwordx4 v[204:207], v217, s[18:19] offset:16
	global_load_dwordx4 v[208:211], v217, s[18:19] offset:512
	global_load_dwordx4 v[212:215], v217, s[18:19] offset:528
	s_lshl_b32 s40, s36, 14
	s_lshl_b32 s41, s31, 4
	s_add_u32 s40, s40, s41
	s_lshl_b32 s41, s59, 2
	s_add_u32 s40, s40, s41
	v_lshl_add_u32 v236, v144, 6, s40
	v_xor_b32_e32 v140, 16, v226
	v_lshlrev_b32_e32 v140, 2, v140
	s_waitcnt vmcnt(12)
	v_pk_add_f32 v[122:123], v[122:123], v[148:149]
	v_pk_add_f32 v[124:125], v[124:125], v[150:151]
	v_pk_add_f32 v[126:127], v[126:127], v[152:153]
	v_pk_add_f32 v[128:129], v[128:129], v[154:155]
	v_pk_add_f32 v[118:119], v[118:119], v[156:157]
	v_pk_add_f32 v[120:121], v[120:121], v[158:159]
	v_pk_add_f32 v[114:115], v[114:115], v[160:161]
	v_pk_add_f32 v[116:117], v[116:117], v[162:163]
	global_store_dwordx4 v198, v[122:125], s[18:19]
	global_store_dwordx4 v198, v[126:129], s[18:19] offset:16
	global_store_dwordx4 v198, v[118:121], s[18:19] offset:512
	global_store_dwordx4 v198, v[114:117], s[18:19] offset:528
	v_cvt_pk_bf16_f32 v148, v122, v123
	v_cvt_pk_bf16_f32 v149, v124, v125
	v_cvt_pk_bf16_f32 v150, v126, v127
	v_cvt_pk_bf16_f32 v151, v128, v129
	v_cvt_pk_bf16_f32 v152, v118, v119
	v_cvt_pk_bf16_f32 v153, v120, v121
	v_cvt_pk_bf16_f32 v154, v114, v115
	v_cvt_pk_bf16_f32 v155, v116, v117
	v_lshrrev_b32_e32 v141, 1, v198
	global_store_dwordx4 v141, v[148:151], s[22:23]
	global_store_dwordx4 v141, v[152:155], s[22:23] offset:256
	v_mul_f32_e32 v142, v123, v123
	v_fmac_f32_e32 v142, v122, v122
	v_mul_f32_e32 v143, v125, v125
	v_fmac_f32_e32 v143, v124, v124
	v_add_f32_e32 v143, v142, v143
	v_mul_f32_e32 v142, v127, v127
	v_fmac_f32_e32 v142, v126, v126
	v_add_f32_e32 v143, v143, v142
	v_mul_f32_e32 v142, v129, v129
	v_fmac_f32_e32 v142, v128, v128
	v_add_f32_e32 v237, v142, v143
	v_mul_f32_e32 v142, v119, v119
	v_fmac_f32_e32 v142, v118, v118
	v_mul_f32_e32 v143, v121, v121
	v_fmac_f32_e32 v143, v120, v120
	v_add_f32_e32 v143, v142, v143
	v_mul_f32_e32 v142, v115, v115
	v_fmac_f32_e32 v142, v114, v114
	v_add_f32_e32 v143, v143, v142
	v_mul_f32_e32 v142, v117, v117
	v_fmac_f32_e32 v142, v116, v116
	v_add_f32_e32 v143, v142, v143
	v_add_f32_e32 v122, v237, v143
	ds_bpermute_b32 v123, v140, v122
	global_load_dwordx4 v[148:151], v218, s[18:19]
	global_load_dwordx4 v[152:155], v218, s[18:19] offset:16
	global_load_dwordx4 v[156:159], v218, s[18:19] offset:512
	global_load_dwordx4 v[160:163], v218, s[18:19] offset:528
	s_waitcnt vmcnt(18)
	v_pk_add_f32 v[110:111], v[110:111], v[164:165]
	v_pk_add_f32 v[112:113], v[112:113], v[166:167]
	v_pk_add_f32 v[106:107], v[106:107], v[168:169]
	v_pk_add_f32 v[108:109], v[108:109], v[170:171]
	v_pk_add_f32 v[102:103], v[102:103], v[172:173]
	v_pk_add_f32 v[104:105], v[104:105], v[174:175]
	v_pk_add_f32 v[98:99], v[98:99], v[176:177]
	v_pk_add_f32 v[100:101], v[100:101], v[178:179]
	global_store_dwordx4 v199, v[110:113], s[18:19]
	global_store_dwordx4 v199, v[106:109], s[18:19] offset:16
	global_store_dwordx4 v199, v[102:105], s[18:19] offset:512
	global_store_dwordx4 v199, v[98:101], s[18:19] offset:528
	v_cvt_pk_bf16_f32 v164, v110, v111
	v_cvt_pk_bf16_f32 v165, v112, v113
	v_cvt_pk_bf16_f32 v166, v106, v107
	v_cvt_pk_bf16_f32 v167, v108, v109
	v_cvt_pk_bf16_f32 v168, v102, v103
	v_cvt_pk_bf16_f32 v169, v104, v105
	v_cvt_pk_bf16_f32 v170, v98, v99
	v_cvt_pk_bf16_f32 v171, v100, v101
	v_lshrrev_b32_e32 v141, 1, v199
	global_store_dwordx4 v141, v[164:167], s[22:23]
	global_store_dwordx4 v141, v[168:171], s[22:23] offset:256
	v_mul_f32_e32 v142, v111, v111
	v_fmac_f32_e32 v142, v110, v110
	v_mul_f32_e32 v143, v113, v113
	v_fmac_f32_e32 v143, v112, v112
	v_add_f32_e32 v143, v142, v143
	v_mul_f32_e32 v142, v107, v107
	v_fmac_f32_e32 v142, v106, v106
	v_add_f32_e32 v143, v143, v142
	v_mul_f32_e32 v142, v109, v109
	v_fmac_f32_e32 v142, v108, v108
	v_add_f32_e32 v237, v142, v143
	v_mul_f32_e32 v142, v103, v103
	v_fmac_f32_e32 v142, v102, v102
	v_mul_f32_e32 v143, v105, v105
	v_fmac_f32_e32 v143, v104, v104
	v_add_f32_e32 v143, v142, v143
	v_mul_f32_e32 v142, v99, v99
	v_fmac_f32_e32 v142, v98, v98
	v_add_f32_e32 v143, v143, v142
	v_mul_f32_e32 v142, v101, v101
	v_fmac_f32_e32 v142, v100, v100
	v_add_f32_e32 v143, v142, v143
	v_add_f32_e32 v110, v237, v143
	ds_bpermute_b32 v111, v140, v110
	global_load_dwordx4 v[164:167], v219, s[18:19]
	global_load_dwordx4 v[168:171], v219, s[18:19] offset:16
	global_load_dwordx4 v[172:175], v219, s[18:19] offset:512
	global_load_dwordx4 v[176:179], v219, s[18:19] offset:528
	s_waitcnt vmcnt(24)
; __device__ __forceinline__ u32x4 pack8(f32x4 a, f32x4 b) { u32x4 w; w.x = cvt_pk_bf16(a[0], a[1]); w.y = cvt_pk_bf16(a[2], a[3]); w.z = cvt_pk_bf16(b[0], b[1]); w.w = cvt_pk_bf16(b[2], b[3]); return w; }
; __device__ __forceinline__ void unpack8(u32x4 w, f32x4& a, f32x4& b) { a = (f32x4){bflo(w.x), bfhi(w.x), bflo(w.y), bfhi(w.y)}; b = (f32x4){bflo(w.z), bfhi(w.z), bflo(w.w), bfhi(w.w)}; }
; __device__ __forceinline__ float sigmoidf_(float x) { return __builtin_amdgcn_rcpf(1.f + __builtin_amdgcn_exp2f(-1.4426950408889634f * x)); }
; __device__ __forceinline__ float xhalf_sum(float v) { const auto r_ = __builtin_amdgcn_permlane32_swap(__float_as_uint(v), __float_as_uint(v), false, false); return __uint_as_float(r_[0]) + __uint_as_float(r_[1]); }
; #define EPI_ROWS_END if (m & 1) asm volatile("" ::: "memory"); }
;     __device__ __forceinline__ void operator()(AccRef acc, const Unit& u, int wr, int wc, int fr, int fq) const {
;         const int col0 = u.pn * 256 + wc * 32 + 8 * fq;
;         EPI_ROWS_BEGIN
;             float r = 1.f; if (MODE == 1) r = RSL(u, row);
;             float ss = 0.f;
; #pragma unroll
;             for (int bj = 0; bj < 2; ++bj) {
;                 const size_t off = (size_t)row * 1024 + col0 + bj * 128;
;                 f32x4 a0 = acc[ai][bj][m][0], a1 = acc[ai][bj][m][1];
;                 if (MODE == 1) { f32x4 t0, t1; unpack8(*(const u32x4*)(tp + off), t0, t1);
; #pragma unroll
;                     for (int e = 0; e < 4; ++e) { a0[e] = sigmoidf_(a0[e] * r) * t0[e]; a1[e] = sigmoidf_(a1[e] * r) * t1[e]; } }
;                 const f32x4 n0 = *(const f32x4*)(xold + off) + a0, n1 = *(const f32x4*)(xold + off + 4) + a1;
;                 *(f32x4*)(xf + off) = n0; *(f32x4*)(xf + off + 4) = n1;
;                 if (MODE == 0) *(u32x4*)(xb + off) = pack8(n0, n1);
;                 ss += (n0[0] * n0[0] + n0[1] * n0[1]) + (n0[2] * n0[2] + n0[3] * n0[3]) + (n1[0] * n1[0] + n1[1] * n1[1]) + (n1[2] * n1[2] + n1[3] * n1[3]);
;             }
;             ss += __shfl_xor(ss, 16); ss = xhalf_sum(ss);
;             if (fq == 0) ssq_out[(size_t)row * 16 + u.pn * 4 + wc] = ss;
;         EPI_ROWS_END
	v_pk_add_f32 v[94:95], v[94:95], v[180:181]
	v_pk_add_f32 v[96:97], v[96:97], v[182:183]
	v_pk_add_f32 v[90:91], v[90:91], v[184:185]
	v_pk_add_f32 v[92:93], v[92:93], v[186:187]
	v_pk_add_f32 v[86:87], v[86:87], v[188:189]
	v_pk_add_f32 v[88:89], v[88:89], v[190:191]
	v_pk_add_f32 v[82:83], v[82:83], v[192:193]
	v_pk_add_f32 v[84:85], v[84:85], v[194:195]
	global_store_dwordx4 v216, v[94:97], s[18:19]
	global_store_dwordx4 v216, v[90:93], s[18:19] offset:16
	global_store_dwordx4 v216, v[86:89], s[18:19] offset:512
	global_store_dwordx4 v216, v[82:85], s[18:19] offset:528
	v_cvt_pk_bf16_f32 v180, v94, v95
	v_cvt_pk_bf16_f32 v181, v96, v97
	v_cvt_pk_bf16_f32 v182, v90, v91
	v_cvt_pk_bf16_f32 v183, v92, v93
	v_cvt_pk_bf16_f32 v184, v86, v87
	v_cvt_pk_bf16_f32 v185, v88, v89
	v_cvt_pk_bf16_f32 v186, v82, v83
	v_cvt_pk_bf16_f32 v187, v84, v85
	v_lshrrev_b32_e32 v141, 1, v216
	global_store_dwordx4 v141, v[180:183], s[22:23]
	global_store_dwordx4 v141, v[184:187], s[22:23] offset:256
	v_mul_f32_e32 v142, v95, v95
	v_fmac_f32_e32 v142, v94, v94
	v_mul_f32_e32 v143, v97, v97
	v_fmac_f32_e32 v143, v96, v96
	v_add_f32_e32 v143, v142, v143
	v_mul_f32_e32 v142, v91, v91
	v_fmac_f32_e32 v142, v90, v90
	v_add_f32_e32 v143, v143, v142
	v_mul_f32_e32 v142, v93, v93
	v_fmac_f32_e32 v142, v92, v92
	v_add_f32_e32 v237, v142, v143
	v_mul_f32_e32 v142, v87, v87
	v_fmac_f32_e32 v142, v86, v86
	v_mul_f32_e32 v143, v89, v89
	v_fmac_f32_e32 v143, v88, v88
	v_add_f32_e32 v143, v142, v143
	v_mul_f32_e32 v142, v83, v83
	v_fmac_f32_e32 v142, v82, v82
	v_add_f32_e32 v143, v143, v142
	v_mul_f32_e32 v142, v85, v85
	v_fmac_f32_e32 v142, v84, v84
	v_add_f32_e32 v143, v142, v143
	v_add_f32_e32 v94, v237, v143
	ds_bpermute_b32 v95, v140, v94
	global_load_dwordx4 v[180:183], v220, s[18:19]
	global_load_dwordx4 v[184:187], v220, s[18:19] offset:16
	global_load_dwordx4 v[188:191], v220, s[18:19] offset:512
	global_load_dwordx4 v[192:195], v220, s[18:19] offset:528
	s_waitcnt vmcnt(30)
	v_pk_add_f32 v[78:79], v[78:79], v[200:201]
	v_pk_add_f32 v[80:81], v[80:81], v[202:203]
	v_pk_add_f32 v[74:75], v[74:75], v[204:205]
	v_pk_add_f32 v[76:77], v[76:77], v[206:207]
	v_pk_add_f32 v[70:71], v[70:71], v[208:209]
	v_pk_add_f32 v[72:73], v[72:73], v[210:211]
	v_pk_add_f32 v[66:67], v[66:67], v[212:213]
	v_pk_add_f32 v[68:69], v[68:69], v[214:215]
	global_store_dwordx4 v217, v[78:81], s[18:19]
	global_store_dwordx4 v217, v[74:77], s[18:19] offset:16
	global_store_dwordx4 v217, v[70:73], s[18:19] offset:512
	global_store_dwordx4 v217, v[66:69], s[18:19] offset:528
	v_cvt_pk_bf16_f32 v200, v78, v79
	v_cvt_pk_bf16_f32 v201, v80, v81
	v_cvt_pk_bf16_f32 v202, v74, v75
	v_cvt_pk_bf16_f32 v203, v76, v77
	v_cvt_pk_bf16_f32 v204, v70, v71
	v_cvt_pk_bf16_f32 v205, v72, v73
	v_cvt_pk_bf16_f32 v206, v66, v67
	v_cvt_pk_bf16_f32 v207, v68, v69
	v_lshrrev_b32_e32 v141, 1, v217
	global_store_dwordx4 v141, v[200:203], s[22:23]
	global_store_dwordx4 v141, v[204:207], s[22:23] offset:256
	v_mul_f32_e32 v142, v79, v79
	v_fmac_f32_e32 v142, v78, v78
	v_mul_f32_e32 v143, v81, v81
	v_fmac_f32_e32 v143, v80, v80
	v_add_f32_e32 v143, v142, v143
	v_mul_f32_e32 v142, v75, v75
	v_fmac_f32_e32 v142, v74, v74
	v_add_f32_e32 v143, v143, v142
	v_mul_f32_e32 v142, v77, v77
	v_fmac_f32_e32 v142, v76, v76
	v_add_f32_e32 v237, v142, v143
	v_mul_f32_e32 v142, v71, v71
	v_fmac_f32_e32 v142, v70, v70
	v_mul_f32_e32 v143, v73, v73
	v_fmac_f32_e32 v143, v72, v72
	v_add_f32_e32 v143, v142, v143
	v_mul_f32_e32 v142, v67, v67
	v_fmac_f32_e32 v142, v66, v66
	v_add_f32_e32 v143, v143, v142
	v_mul_f32_e32 v142, v69, v69
	v_fmac_f32_e32 v142, v68, v68
	v_add_f32_e32 v143, v142, v143
	v_add_f32_e32 v78, v237, v143
	ds_bpermute_b32 v79, v140, v78
	global_load_dwordx4 v[200:203], v221, s[18:19]
	global_load_dwordx4 v[204:207], v221, s[18:19] offset:16
	global_load_dwordx4 v[208:211], v221, s[18:19] offset:512
	global_load_dwordx4 v[212:215], v221, s[18:19] offset:528
	s_waitcnt vmcnt(30)
	v_pk_add_f32 v[62:63], v[62:63], v[148:149]
	v_pk_add_f32 v[64:65], v[64:65], v[150:151]
	v_pk_add_f32 v[58:59], v[58:59], v[152:153]
	v_pk_add_f32 v[60:61], v[60:61], v[154:155]
	v_pk_add_f32 v[54:55], v[54:55], v[156:157]
	v_pk_add_f32 v[56:57], v[56:57], v[158:159]
	v_pk_add_f32 v[50:51], v[50:51], v[160:161]
	v_pk_add_f32 v[52:53], v[52:53], v[162:163]
	global_store_dwordx4 v218, v[62:65], s[18:19]
	global_store_dwordx4 v218, v[58:61], s[18:19] offset:16
	global_store_dwordx4 v218, v[54:57], s[18:19] offset:512
	global_store_dwordx4 v218, v[50:53], s[18:19] offset:528
	v_cvt_pk_bf16_f32 v148, v62, v63
	v_cvt_pk_bf16_f32 v149, v64, v65
	v_cvt_pk_bf16_f32 v150, v58, v59
	v_cvt_pk_bf16_f32 v151, v60, v61
	v_cvt_pk_bf16_f32 v152, v54, v55
	v_cvt_pk_bf16_f32 v153, v56, v57
	v_cvt_pk_bf16_f32 v154, v50, v51
	v_cvt_pk_bf16_f32 v155, v52, v53
	v_lshrrev_b32_e32 v141, 1, v218
	global_store_dwordx4 v141, v[148:151], s[22:23]
	global_store_dwordx4 v141, v[152:155], s[22:23] offset:256
	v_mul_f32_e32 v142, v63, v63
	v_fmac_f32_e32 v142, v62, v62
	v_mul_f32_e32 v143, v65, v65
	v_fmac_f32_e32 v143, v64, v64
	v_add_f32_e32 v143, v142, v143
	v_mul_f32_e32 v142, v59, v59
	v_fmac_f32_e32 v142, v58, v58
	v_add_f32_e32 v143, v143, v142
	v_mul_f32_e32 v142, v61, v61
	v_fmac_f32_e32 v142, v60, v60
	v_add_f32_e32 v237, v142, v143
	v_mul_f32_e32 v142, v55, v55
	v_fmac_f32_e32 v142, v54, v54
	v_mul_f32_e32 v143, v57, v57
	v_fmac_f32_e32 v143, v56, v56
	v_add_f32_e32 v143, v142, v143
	v_mul_f32_e32 v142, v51, v51
	v_fmac_f32_e32 v142, v50, v50
	v_add_f32_e32 v143, v143, v142
	v_mul_f32_e32 v142, v53, v53
	v_fmac_f32_e32 v142, v52, v52
	v_add_f32_e32 v143, v142, v143
	v_add_f32_e32 v62, v237, v143
	ds_bpermute_b32 v63, v140, v62
	s_waitcnt vmcnt(26)
; __device__ __forceinline__ u32x4 pack8(f32x4 a, f32x4 b) { u32x4 w; w.x = cvt_pk_bf16(a[0], a[1]); w.y = cvt_pk_bf16(a[2], a[3]); w.z = cvt_pk_bf16(b[0], b[1]); w.w = cvt_pk_bf16(b[2], b[3]); return w; }
; __device__ __forceinline__ void unpack8(u32x4 w, f32x4& a, f32x4& b) { a = (f32x4){bflo(w.x), bfhi(w.x), bflo(w.y), bfhi(w.y)}; b = (f32x4){bflo(w.z), bfhi(w.z), bflo(w.w), bfhi(w.w)}; }
; __device__ __forceinline__ float sigmoidf_(float x) { return __builtin_amdgcn_rcpf(1.f + __builtin_amdgcn_exp2f(-1.4426950408889634f * x)); }
; __device__ __forceinline__ float xhalf_sum(float v) { const auto r_ = __builtin_amdgcn_permlane32_swap(__float_as_uint(v), __float_as_uint(v), false, false); return __uint_as_float(r_[0]) + __uint_as_float(r_[1]); }
; #define EPI_ROWS_END if (m & 1) asm volatile("" ::: "memory"); }
;     __device__ __forceinline__ void operator()(AccRef acc, const Unit& u, int wr, int wc, int fr, int fq) const {
;         const int col0 = u.pn * 256 + wc * 32 + 8 * fq;
;         EPI_ROWS_BEGIN
;             float r = 1.f; if (MODE == 1) r = RSL(u, row);
;             float ss = 0.f;
; #pragma unroll
;             for (int bj = 0; bj < 2; ++bj) {
;                 const size_t off = (size_t)row * 1024 + col0 + bj * 128;
;                 f32x4 a0 = acc[ai][bj][m][0], a1 = acc[ai][bj][m][1];
;                 if (MODE == 1) { f32x4 t0, t1; unpack8(*(const u32x4*)(tp + off), t0, t1);
; #pragma unroll
;                     for (int e = 0; e < 4; ++e) { a0[e] = sigmoidf_(a0[e] * r) * t0[e]; a1[e] = sigmoidf_(a1[e] * r) * t1[e]; } }
;                 const f32x4 n0 = *(const f32x4*)(xold + off) + a0, n1 = *(const f32x4*)(xold + off + 4) + a1;
;                 *(f32x4*)(xf + off) = n0; *(f32x4*)(xf + off + 4) = n1;
;                 if (MODE == 0) *(u32x4*)(xb + off) = pack8(n0, n1);
;                 ss += (n0[0] * n0[0] + n0[1] * n0[1]) + (n0[2] * n0[2] + n0[3] * n0[3]) + (n1[0] * n1[0] + n1[1] * n1[1]) + (n1[2] * n1[2] + n1[3] * n1[3]);
;             }
;             ss += __shfl_xor(ss, 16); ss = xhalf_sum(ss);
;             if (fq == 0) ssq_out[(size_t)row * 16 + u.pn * 4 + wc] = ss;
;         EPI_ROWS_END
	v_pk_add_f32 v[46:47], v[46:47], v[164:165]
	v_pk_add_f32 v[48:49], v[48:49], v[166:167]
	v_pk_add_f32 v[42:43], v[42:43], v[168:169]
	v_pk_add_f32 v[44:45], v[44:45], v[170:171]
	v_pk_add_f32 v[38:39], v[38:39], v[172:173]
	v_pk_add_f32 v[40:41], v[40:41], v[174:175]
	v_pk_add_f32 v[34:35], v[34:35], v[176:177]
	v_pk_add_f32 v[36:37], v[36:37], v[178:179]
	global_store_dwordx4 v219, v[46:49], s[18:19]
	global_store_dwordx4 v219, v[42:45], s[18:19] offset:16
	global_store_dwordx4 v219, v[38:41], s[18:19] offset:512
	global_store_dwordx4 v219, v[34:37], s[18:19] offset:528
	v_cvt_pk_bf16_f32 v164, v46, v47
	v_cvt_pk_bf16_f32 v165, v48, v49
	v_cvt_pk_bf16_f32 v166, v42, v43
	v_cvt_pk_bf16_f32 v167, v44, v45
	v_cvt_pk_bf16_f32 v168, v38, v39
	v_cvt_pk_bf16_f32 v169, v40, v41
	v_cvt_pk_bf16_f32 v170, v34, v35
	v_cvt_pk_bf16_f32 v171, v36, v37
	v_lshrrev_b32_e32 v141, 1, v219
	global_store_dwordx4 v141, v[164:167], s[22:23]
	global_store_dwordx4 v141, v[168:171], s[22:23] offset:256
	v_mul_f32_e32 v142, v47, v47
	v_fmac_f32_e32 v142, v46, v46
	v_mul_f32_e32 v143, v49, v49
	v_fmac_f32_e32 v143, v48, v48
	v_add_f32_e32 v143, v142, v143
	v_mul_f32_e32 v142, v43, v43
	v_fmac_f32_e32 v142, v42, v42
	v_add_f32_e32 v143, v143, v142
	v_mul_f32_e32 v142, v45, v45
	v_fmac_f32_e32 v142, v44, v44
	v_add_f32_e32 v237, v142, v143
	v_mul_f32_e32 v142, v39, v39
	v_fmac_f32_e32 v142, v38, v38
	v_mul_f32_e32 v143, v41, v41
	v_fmac_f32_e32 v143, v40, v40
	v_add_f32_e32 v143, v142, v143
	v_mul_f32_e32 v142, v35, v35
	v_fmac_f32_e32 v142, v34, v34
	v_add_f32_e32 v143, v143, v142
	v_mul_f32_e32 v142, v37, v37
	v_fmac_f32_e32 v142, v36, v36
	v_add_f32_e32 v143, v142, v143
	v_add_f32_e32 v46, v237, v143
	ds_bpermute_b32 v47, v140, v46
	s_waitcnt vmcnt(22)
	v_pk_add_f32 v[30:31], v[30:31], v[180:181]
	v_pk_add_f32 v[32:33], v[32:33], v[182:183]
	v_pk_add_f32 v[26:27], v[26:27], v[184:185]
	v_pk_add_f32 v[28:29], v[28:29], v[186:187]
	v_pk_add_f32 v[22:23], v[22:23], v[188:189]
	v_pk_add_f32 v[24:25], v[24:25], v[190:191]
	v_pk_add_f32 v[18:19], v[18:19], v[192:193]
	v_pk_add_f32 v[20:21], v[20:21], v[194:195]
	global_store_dwordx4 v220, v[30:33], s[18:19]
	global_store_dwordx4 v220, v[26:29], s[18:19] offset:16
	global_store_dwordx4 v220, v[22:25], s[18:19] offset:512
	global_store_dwordx4 v220, v[18:21], s[18:19] offset:528
	v_cvt_pk_bf16_f32 v180, v30, v31
	v_cvt_pk_bf16_f32 v181, v32, v33
	v_cvt_pk_bf16_f32 v182, v26, v27
	v_cvt_pk_bf16_f32 v183, v28, v29
	v_cvt_pk_bf16_f32 v184, v22, v23
	v_cvt_pk_bf16_f32 v185, v24, v25
	v_cvt_pk_bf16_f32 v186, v18, v19
	v_cvt_pk_bf16_f32 v187, v20, v21
	v_lshrrev_b32_e32 v141, 1, v220
	global_store_dwordx4 v141, v[180:183], s[22:23]
	global_store_dwordx4 v141, v[184:187], s[22:23] offset:256
	v_mul_f32_e32 v142, v31, v31
	v_fmac_f32_e32 v142, v30, v30
	v_mul_f32_e32 v143, v33, v33
	v_fmac_f32_e32 v143, v32, v32
	v_add_f32_e32 v143, v142, v143
	v_mul_f32_e32 v142, v27, v27
	v_fmac_f32_e32 v142, v26, v26
	v_add_f32_e32 v143, v143, v142
	v_mul_f32_e32 v142, v29, v29
	v_fmac_f32_e32 v142, v28, v28
	v_add_f32_e32 v237, v142, v143
	v_mul_f32_e32 v142, v23, v23
	v_fmac_f32_e32 v142, v22, v22
	v_mul_f32_e32 v143, v25, v25
	v_fmac_f32_e32 v143, v24, v24
	v_add_f32_e32 v143, v142, v143
	v_mul_f32_e32 v142, v19, v19
	v_fmac_f32_e32 v142, v18, v18
	v_add_f32_e32 v143, v143, v142
	v_mul_f32_e32 v142, v21, v21
	v_fmac_f32_e32 v142, v20, v20
	v_add_f32_e32 v143, v142, v143
	v_add_f32_e32 v30, v237, v143
	ds_bpermute_b32 v31, v140, v30
	s_waitcnt vmcnt(18)
	v_pk_add_f32 v[14:15], v[14:15], v[200:201]
	v_pk_add_f32 v[16:17], v[16:17], v[202:203]
	v_pk_add_f32 v[10:11], v[10:11], v[204:205]
	v_pk_add_f32 v[12:13], v[12:13], v[206:207]
	v_pk_add_f32 v[6:7], v[6:7], v[208:209]
	v_pk_add_f32 v[8:9], v[8:9], v[210:211]
	v_pk_add_f32 v[2:3], v[2:3], v[212:213]
	v_pk_add_f32 v[4:5], v[4:5], v[214:215]
	global_store_dwordx4 v221, v[14:17], s[18:19]
	global_store_dwordx4 v221, v[10:13], s[18:19] offset:16
	global_store_dwordx4 v221, v[6:9], s[18:19] offset:512
	global_store_dwordx4 v221, v[2:5], s[18:19] offset:528
	v_cvt_pk_bf16_f32 v200, v14, v15
	v_cvt_pk_bf16_f32 v201, v16, v17
	v_cvt_pk_bf16_f32 v202, v10, v11
	v_cvt_pk_bf16_f32 v203, v12, v13
	v_cvt_pk_bf16_f32 v204, v6, v7
	v_cvt_pk_bf16_f32 v205, v8, v9
	v_cvt_pk_bf16_f32 v206, v2, v3
	v_cvt_pk_bf16_f32 v207, v4, v5
	v_lshrrev_b32_e32 v141, 1, v221
	global_store_dwordx4 v141, v[200:203], s[22:23]
	global_store_dwordx4 v141, v[204:207], s[22:23] offset:256
	v_mul_f32_e32 v142, v15, v15
	v_fmac_f32_e32 v142, v14, v14
	v_mul_f32_e32 v143, v17, v17
	v_fmac_f32_e32 v143, v16, v16
	v_add_f32_e32 v143, v142, v143
	v_mul_f32_e32 v142, v11, v11
	v_fmac_f32_e32 v142, v10, v10
	v_add_f32_e32 v143, v143, v142
	v_mul_f32_e32 v142, v13, v13
	v_fmac_f32_e32 v142, v12, v12
	v_add_f32_e32 v237, v142, v143
	v_mul_f32_e32 v142, v7, v7
	v_fmac_f32_e32 v142, v6, v6
	v_mul_f32_e32 v143, v9, v9
	v_fmac_f32_e32 v143, v8, v8
	v_add_f32_e32 v143, v142, v143
	v_mul_f32_e32 v142, v3, v3
	v_fmac_f32_e32 v142, v2, v2
	v_add_f32_e32 v143, v143, v142
	v_mul_f32_e32 v142, v5, v5
	v_fmac_f32_e32 v142, v4, v4
	v_add_f32_e32 v143, v142, v143
	v_add_f32_e32 v14, v237, v143
	ds_bpermute_b32 v15, v140, v14
	s_waitcnt lgkmcnt(0)
	v_add_f32_e32 v122, v122, v123
	v_add_f32_e32 v110, v110, v111
	v_add_f32_e32 v94, v94, v95
	v_add_f32_e32 v78, v78, v79
	v_add_f32_e32 v62, v62, v63
	v_add_f32_e32 v46, v46, v47
	v_add_f32_e32 v30, v30, v31
	v_add_f32_e32 v14, v14, v15
	v_mov_b32_e32 v123, v122
	v_mov_b32_e32 v111, v110
	v_mov_b32_e32 v95, v94
	v_mov_b32_e32 v79, v78
	v_mov_b32_e32 v63, v62
	v_mov_b32_e32 v47, v46
	v_mov_b32_e32 v31, v30
	v_mov_b32_e32 v15, v14
	s_nop 1
	v_permlane32_swap_b32_e32 v122, v123
	v_permlane32_swap_b32_e32 v110, v111
	v_permlane32_swap_b32_e32 v94, v95
	v_permlane32_swap_b32_e32 v78, v79
	v_permlane32_swap_b32_e32 v62, v63
	v_permlane32_swap_b32_e32 v46, v47
	v_permlane32_swap_b32_e32 v30, v31
	v_permlane32_swap_b32_e32 v14, v15
	v_add_f32_e32 v122, v122, v123
	v_add_f32_e32 v110, v110, v111
	v_add_f32_e32 v94, v94, v95
	v_add_f32_e32 v78, v78, v79
	v_add_f32_e32 v62, v62, v63
	v_add_f32_e32 v46, v46, v47
	v_add_f32_e32 v30, v30, v31
	v_add_f32_e32 v14, v14, v15
	s_and_saveexec_b64 s[38:39], s[44:45]
	global_store_dword v236, v122, s[24:25]
	v_add_u32_e32 v141, 0x400, v236
	global_store_dword v141, v110, s[24:25]
	v_add_u32_e32 v141, 0x800, v236
	global_store_dword v141, v94, s[24:25]
	v_add_u32_e32 v141, 0xc00, v236
	global_store_dword v141, v78, s[24:25]
	v_add_u32_e32 v141, 0x2000, v236
	global_store_dword v141, v62, s[24:25]
	v_add_u32_e32 v141, 0x2400, v236
	global_store_dword v141, v46, s[24:25]
	v_add_u32_e32 v141, 0x2800, v236
	global_store_dword v141, v30, s[24:25]
	v_add_u32_e32 v141, 0x2c00, v236
	global_store_dword v141, v14, s[24:25]
	s_or_b64 exec, exec, s[38:39]
	s_and_b64 vcc, exec, s[46:47]
	s_mov_b64 s[38:39], -1
	s_cbranch_vccnz .LBB0_1632
	s_andn2_b64 vcc, exec, s[20:21]
	s_cbranch_vccnz .LBB0_1631
	s_barrier
	s_branch .LBB0_1631

; __device__ __forceinline__ u32x4 pack8(f32x4 a, f32x4 b) { u32x4 w; w.x = cvt_pk_bf16(a[0], a[1]); w.y = cvt_pk_bf16(a[2], a[3]); w.z = cvt_pk_bf16(b[0], b[1]); w.w = cvt_pk_bf16(b[2], b[3]); return w; }
; __device__ __forceinline__ void unpack8(u32x4 w, f32x4& a, f32x4& b) { a = (f32x4){bflo(w.x), bfhi(w.x), bflo(w.y), bfhi(w.y)}; b = (f32x4){bflo(w.z), bfhi(w.z), bflo(w.w), bfhi(w.w)}; }
; __device__ __forceinline__ float sigmoidf_(float x) { return __builtin_amdgcn_rcpf(1.f + __builtin_amdgcn_exp2f(-1.4426950408889634f * x)); }
; __device__ __forceinline__ float xhalf_sum(float v) { const auto r_ = __builtin_amdgcn_permlane32_swap(__float_as_uint(v), __float_as_uint(v), false, false); return __uint_as_float(r_[0]) + __uint_as_float(r_[1]); }
; #define EPI_ROWS_END if (m & 1) asm volatile("" ::: "memory"); }
;     __device__ __forceinline__ void operator()(AccRef acc, const Unit& u, int wr, int wc, int fr, int fq) const {
;         const int col0 = u.pn * 256 + wc * 32 + 8 * fq;
;         EPI_ROWS_BEGIN
;             float r = 1.f; if (MODE == 1) r = RSL(u, row);
;             float ss = 0.f;
; #pragma unroll
;             for (int bj = 0; bj < 2; ++bj) {
;                 const size_t off = (size_t)row * 1024 + col0 + bj * 128;
;                 f32x4 a0 = acc[ai][bj][m][0], a1 = acc[ai][bj][m][1];
;                 if (MODE == 1) { f32x4 t0, t1; unpack8(*(const u32x4*)(tp + off), t0, t1);
; #pragma unroll
;                     for (int e = 0; e < 4; ++e) { a0[e] = sigmoidf_(a0[e] * r) * t0[e]; a1[e] = sigmoidf_(a1[e] * r) * t1[e]; } }
;                 const f32x4 n0 = *(const f32x4*)(xold + off) + a0, n1 = *(const f32x4*)(xold + off + 4) + a1;
;                 *(f32x4*)(xf + off) = n0; *(f32x4*)(xf + off + 4) = n1;
;                 if (MODE == 0) *(u32x4*)(xb + off) = pack8(n0, n1);
;                 ss += (n0[0] * n0[0] + n0[1] * n0[1]) + (n0[2] * n0[2] + n0[3] * n0[3]) + (n1[0] * n1[0] + n1[1] * n1[1]) + (n1[2] * n1[2] + n1[3] * n1[3]);
;             }
;             ss += __shfl_xor(ss, 16); ss = xhalf_sum(ss);
;             if (fq == 0) ssq_out[(size_t)row * 16 + u.pn * 4 + wc] = ss;
;         EPI_ROWS_END
.LBB0_1776:
	s_waitcnt lgkmcnt(0)
	s_lshl_b32 s64, s31, 20
	s_lshl_b32 s65, s60, 10
	s_add_u32 s64, s64, s65
	v_lshlrev_b32_e32 v145, 12, v146
	v_lshl_add_u32 v145, v148, 2, v145
	v_add_u32_e32 v144, s64, v145
	s_lshl_b32 s38, s36, 10
	s_add_i32 s38, s38, 0x21000
	v_mov_b32_e32 v145, v144
	v_lshrrev_b32_e32 v198, 1, v145
	global_load_dwordx4 v[140:143], v198, s[10:11]
	global_load_dwordx4 v[160:163], v198, s[10:11] offset:256
	global_load_dwordx4 v[164:167], v145, s[8:9]
	global_load_dwordx4 v[168:171], v145, s[8:9] offset:16
	global_load_dwordx4 v[172:175], v145, s[8:9] offset:512
	global_load_dwordx4 v[176:179], v145, s[8:9] offset:528
	v_add_u32_e32 v145, 0x10000, v144
	v_lshrrev_b32_e32 v198, 1, v145
	global_load_dwordx4 v[180:183], v198, s[10:11]
	global_load_dwordx4 v[184:187], v198, s[10:11] offset:256
	global_load_dwordx4 v[188:191], v145, s[8:9]
	global_load_dwordx4 v[192:195], v145, s[8:9] offset:16
	global_load_dwordx4 v[200:203], v145, s[8:9] offset:512
	global_load_dwordx4 v[204:207], v145, s[8:9] offset:528
	v_add_u32_e32 v145, 0x20000, v144
	v_lshrrev_b32_e32 v198, 1, v145
	global_load_dwordx4 v[208:211], v198, s[10:11]
	global_load_dwordx4 v[212:215], v198, s[10:11] offset:256
	global_load_dwordx4 v[216:219], v145, s[8:9]
	global_load_dwordx4 v[236:239], v145, s[8:9] offset:16
	global_load_dwordx4 v[240:243], v145, s[8:9] offset:512
	global_load_dwordx4 v[244:247], v145, s[8:9] offset:528
	v_lshl_add_u32 v199, v146, 2, s38
	ds_read_b32 v159, v199 offset:0
	s_waitcnt lgkmcnt(0)
	v_mul_f32_e32 v122, v122, v159
	v_mul_f32_e32 v123, v123, v159
	v_mul_f32_e32 v124, v124, v159
	v_mul_f32_e32 v125, v125, v159
	v_mul_f32_e32 v126, v126, v159
	v_mul_f32_e32 v127, v127, v159
	v_mul_f32_e32 v128, v128, v159
	v_mul_f32_e32 v129, v129, v159
	v_mul_f32_e32 v118, v118, v159
	v_mul_f32_e32 v119, v119, v159
	v_mul_f32_e32 v120, v120, v159
	v_mul_f32_e32 v121, v121, v159
	v_mul_f32_e32 v114, v114, v159
	v_mul_f32_e32 v115, v115, v159
	v_mul_f32_e32 v116, v116, v159
	v_mul_f32_e32 v117, v117, v159
	v_mul_f32_e32 v122, 0xbfb8aa3b, v122
	v_mul_f32_e32 v123, 0xbfb8aa3b, v123
	v_mul_f32_e32 v124, 0xbfb8aa3b, v124
	v_mul_f32_e32 v125, 0xbfb8aa3b, v125
	v_mul_f32_e32 v126, 0xbfb8aa3b, v126
	v_mul_f32_e32 v127, 0xbfb8aa3b, v127
	v_mul_f32_e32 v128, 0xbfb8aa3b, v128
	v_mul_f32_e32 v129, 0xbfb8aa3b, v129
	v_mul_f32_e32 v118, 0xbfb8aa3b, v118
	v_mul_f32_e32 v119, 0xbfb8aa3b, v119
	v_mul_f32_e32 v120, 0xbfb8aa3b, v120
	v_mul_f32_e32 v121, 0xbfb8aa3b, v121
	v_mul_f32_e32 v114, 0xbfb8aa3b, v114
	v_mul_f32_e32 v115, 0xbfb8aa3b, v115
	v_mul_f32_e32 v116, 0xbfb8aa3b, v116
	v_mul_f32_e32 v117, 0xbfb8aa3b, v117
	v_exp_f32_e32 v122, v122
	v_exp_f32_e32 v123, v123
	v_exp_f32_e32 v124, v124
	v_exp_f32_e32 v125, v125
	v_exp_f32_e32 v126, v126
	v_exp_f32_e32 v127, v127
	v_exp_f32_e32 v128, v128
	v_exp_f32_e32 v129, v129
	v_exp_f32_e32 v118, v118
	v_exp_f32_e32 v119, v119
	v_exp_f32_e32 v120, v120
	v_exp_f32_e32 v121, v121
	v_exp_f32_e32 v114, v114
	v_exp_f32_e32 v115, v115
	v_exp_f32_e32 v116, v116
	v_exp_f32_e32 v117, v117
	v_add_f32_e32 v122, 1.0, v122
	v_add_f32_e32 v123, 1.0, v123
	v_add_f32_e32 v124, 1.0, v124
	v_add_f32_e32 v125, 1.0, v125
	v_add_f32_e32 v126, 1.0, v126
	v_add_f32_e32 v127, 1.0, v127
	v_add_f32_e32 v128, 1.0, v128
	v_add_f32_e32 v129, 1.0, v129
	v_add_f32_e32 v118, 1.0, v118
	v_add_f32_e32 v119, 1.0, v119
	v_add_f32_e32 v120, 1.0, v120
	v_add_f32_e32 v121, 1.0, v121
	v_add_f32_e32 v114, 1.0, v114
	v_add_f32_e32 v115, 1.0, v115
	v_add_f32_e32 v116, 1.0, v116
	v_add_f32_e32 v117, 1.0, v117
	v_rcp_f32_e32 v122, v122
	v_rcp_f32_e32 v123, v123
	v_rcp_f32_e32 v124, v124
	v_rcp_f32_e32 v125, v125
	v_rcp_f32_e32 v126, v126
	v_rcp_f32_e32 v127, v127
	v_rcp_f32_e32 v128, v128
	v_rcp_f32_e32 v129, v129
	v_rcp_f32_e32 v118, v118
	v_rcp_f32_e32 v119, v119
	v_rcp_f32_e32 v120, v120
	v_rcp_f32_e32 v121, v121
	v_rcp_f32_e32 v114, v114
	v_rcp_f32_e32 v115, v115
	v_rcp_f32_e32 v116, v116
	v_rcp_f32_e32 v117, v117
	s_waitcnt vmcnt(12)
	v_lshlrev_b32_e32 v150, 16, v140
	v_and_b32_e32 v151, 0xffff0000, v140
	v_lshlrev_b32_e32 v152, 16, v141
	v_and_b32_e32 v153, 0xffff0000, v141
	v_lshlrev_b32_e32 v154, 16, v142
	v_and_b32_e32 v155, 0xffff0000, v142
	v_lshlrev_b32_e32 v156, 16, v143
	v_and_b32_e32 v157, 0xffff0000, v143
	v_pk_fma_f32 v[164:165], v[122:123], v[150:151], v[164:165]
	v_pk_fma_f32 v[166:167], v[124:125], v[152:153], v[166:167]
	v_pk_fma_f32 v[168:169], v[126:127], v[154:155], v[168:169]
	v_pk_fma_f32 v[170:171], v[128:129], v[156:157], v[170:171]
	v_lshlrev_b32_e32 v150, 16, v160
	v_and_b32_e32 v151, 0xffff0000, v160
	v_lshlrev_b32_e32 v152, 16, v161
	v_and_b32_e32 v153, 0xffff0000, v161
	v_lshlrev_b32_e32 v154, 16, v162
	v_and_b32_e32 v155, 0xffff0000, v162
	v_lshlrev_b32_e32 v156, 16, v163
	v_and_b32_e32 v157, 0xffff0000, v163
	v_pk_fma_f32 v[172:173], v[118:119], v[150:151], v[172:173]
	v_pk_fma_f32 v[174:175], v[120:121], v[152:153], v[174:175]
	v_pk_fma_f32 v[176:177], v[114:115], v[154:155], v[176:177]
	v_pk_fma_f32 v[178:179], v[116:117], v[156:157], v[178:179]
	v_mov_b32_e32 v145, v144
	global_store_dwordx4 v145, v[164:167], s[8:9]
	global_store_dwordx4 v145, v[168:171], s[8:9] offset:16
	global_store_dwordx4 v145, v[172:175], s[8:9] offset:512
	global_store_dwordx4 v145, v[176:179], s[8:9] offset:528
	v_mul_f32_e32 v220, v165, v165
	v_fmac_f32_e32 v220, v164, v164
	v_mul_f32_e32 v221, v167, v167
	v_fmac_f32_e32 v221, v166, v166
	v_add_f32_e32 v221, v220, v221
	v_mul_f32_e32 v220, v169, v169
	v_fmac_f32_e32 v220, v168, v168
	v_add_f32_e32 v221, v221, v220
	v_mul_f32_e32 v220, v171, v171
	v_fmac_f32_e32 v220, v170, v170
	v_add_f32_e32 v199, v220, v221
	v_mul_f32_e32 v220, v173, v173
	v_fmac_f32_e32 v220, v172, v172
	v_mul_f32_e32 v221, v175, v175
	v_fmac_f32_e32 v221, v174, v174
	v_add_f32_e32 v221, v220, v221
	v_mul_f32_e32 v220, v177, v177
	v_fmac_f32_e32 v220, v176, v176
	v_add_f32_e32 v221, v221, v220
	v_mul_f32_e32 v220, v179, v179
	v_fmac_f32_e32 v220, v178, v178
	v_add_f32_e32 v221, v220, v221
	v_add_f32_e32 v122, v199, v221
	v_xor_b32_e32 v220, 16, v226
	v_lshlrev_b32_e32 v220, 2, v220
	ds_bpermute_b32 v123, v220, v122
	v_add_u32_e32 v145, 0x30000, v144
	v_lshrrev_b32_e32 v198, 1, v145
	global_load_dwordx4 v[140:143], v198, s[10:11]
	global_load_dwordx4 v[160:163], v198, s[10:11] offset:256
	global_load_dwordx4 v[164:167], v145, s[8:9]
	global_load_dwordx4 v[168:171], v145, s[8:9] offset:16
	global_load_dwordx4 v[172:175], v145, s[8:9] offset:512
	global_load_dwordx4 v[176:179], v145, s[8:9] offset:528
	v_lshl_add_u32 v199, v146, 2, s38
	ds_read_b32 v159, v199 offset:64
	s_waitcnt lgkmcnt(0)
; __device__ __forceinline__ u32x4 pack8(f32x4 a, f32x4 b) { u32x4 w; w.x = cvt_pk_bf16(a[0], a[1]); w.y = cvt_pk_bf16(a[2], a[3]); w.z = cvt_pk_bf16(b[0], b[1]); w.w = cvt_pk_bf16(b[2], b[3]); return w; }
; __device__ __forceinline__ void unpack8(u32x4 w, f32x4& a, f32x4& b) { a = (f32x4){bflo(w.x), bfhi(w.x), bflo(w.y), bfhi(w.y)}; b = (f32x4){bflo(w.z), bfhi(w.z), bflo(w.w), bfhi(w.w)}; }
; __device__ __forceinline__ float sigmoidf_(float x) { return __builtin_amdgcn_rcpf(1.f + __builtin_amdgcn_exp2f(-1.4426950408889634f * x)); }
; __device__ __forceinline__ float xhalf_sum(float v) { const auto r_ = __builtin_amdgcn_permlane32_swap(__float_as_uint(v), __float_as_uint(v), false, false); return __uint_as_float(r_[0]) + __uint_as_float(r_[1]); }
; #define EPI_ROWS_END if (m & 1) asm volatile("" ::: "memory"); }
;     __device__ __forceinline__ void operator()(AccRef acc, const Unit& u, int wr, int wc, int fr, int fq) const {
;         const int col0 = u.pn * 256 + wc * 32 + 8 * fq;
;         EPI_ROWS_BEGIN
;             float r = 1.f; if (MODE == 1) r = RSL(u, row);
;             float ss = 0.f;
; #pragma unroll
;             for (int bj = 0; bj < 2; ++bj) {
;                 const size_t off = (size_t)row * 1024 + col0 + bj * 128;
;                 f32x4 a0 = acc[ai][bj][m][0], a1 = acc[ai][bj][m][1];
;                 if (MODE == 1) { f32x4 t0, t1; unpack8(*(const u32x4*)(tp + off), t0, t1);
; #pragma unroll
;                     for (int e = 0; e < 4; ++e) { a0[e] = sigmoidf_(a0[e] * r) * t0[e]; a1[e] = sigmoidf_(a1[e] * r) * t1[e]; } }
;                 const f32x4 n0 = *(const f32x4*)(xold + off) + a0, n1 = *(const f32x4*)(xold + off + 4) + a1;
;                 *(f32x4*)(xf + off) = n0; *(f32x4*)(xf + off + 4) = n1;
;                 if (MODE == 0) *(u32x4*)(xb + off) = pack8(n0, n1);
;                 ss += (n0[0] * n0[0] + n0[1] * n0[1]) + (n0[2] * n0[2] + n0[3] * n0[3]) + (n1[0] * n1[0] + n1[1] * n1[1]) + (n1[2] * n1[2] + n1[3] * n1[3]);
;             }
;             ss += __shfl_xor(ss, 16); ss = xhalf_sum(ss);
;             if (fq == 0) ssq_out[(size_t)row * 16 + u.pn * 4 + wc] = ss;
;         EPI_ROWS_END
	v_mul_f32_e32 v110, v110, v159
	v_mul_f32_e32 v111, v111, v159
	v_mul_f32_e32 v112, v112, v159
	v_mul_f32_e32 v113, v113, v159
	v_mul_f32_e32 v106, v106, v159
	v_mul_f32_e32 v107, v107, v159
	v_mul_f32_e32 v108, v108, v159
	v_mul_f32_e32 v109, v109, v159
	v_mul_f32_e32 v102, v102, v159
	v_mul_f32_e32 v103, v103, v159
	v_mul_f32_e32 v104, v104, v159
	v_mul_f32_e32 v105, v105, v159
	v_mul_f32_e32 v98, v98, v159
	v_mul_f32_e32 v99, v99, v159
	v_mul_f32_e32 v100, v100, v159
	v_mul_f32_e32 v101, v101, v159
	v_mul_f32_e32 v110, 0xbfb8aa3b, v110
	v_mul_f32_e32 v111, 0xbfb8aa3b, v111
	v_mul_f32_e32 v112, 0xbfb8aa3b, v112
	v_mul_f32_e32 v113, 0xbfb8aa3b, v113
	v_mul_f32_e32 v106, 0xbfb8aa3b, v106
	v_mul_f32_e32 v107, 0xbfb8aa3b, v107
	v_mul_f32_e32 v108, 0xbfb8aa3b, v108
	v_mul_f32_e32 v109, 0xbfb8aa3b, v109
	v_mul_f32_e32 v102, 0xbfb8aa3b, v102
	v_mul_f32_e32 v103, 0xbfb8aa3b, v103
	v_mul_f32_e32 v104, 0xbfb8aa3b, v104
	v_mul_f32_e32 v105, 0xbfb8aa3b, v105
	v_mul_f32_e32 v98, 0xbfb8aa3b, v98
	v_mul_f32_e32 v99, 0xbfb8aa3b, v99
	v_mul_f32_e32 v100, 0xbfb8aa3b, v100
	v_mul_f32_e32 v101, 0xbfb8aa3b, v101
	v_exp_f32_e32 v110, v110
	v_exp_f32_e32 v111, v111
	v_exp_f32_e32 v112, v112
	v_exp_f32_e32 v113, v113
	v_exp_f32_e32 v106, v106
	v_exp_f32_e32 v107, v107
	v_exp_f32_e32 v108, v108
	v_exp_f32_e32 v109, v109
	v_exp_f32_e32 v102, v102
	v_exp_f32_e32 v103, v103
	v_exp_f32_e32 v104, v104
	v_exp_f32_e32 v105, v105
	v_exp_f32_e32 v98, v98
	v_exp_f32_e32 v99, v99
	v_exp_f32_e32 v100, v100
	v_exp_f32_e32 v101, v101
	v_add_f32_e32 v110, 1.0, v110
	v_add_f32_e32 v111, 1.0, v111
	v_add_f32_e32 v112, 1.0, v112
	v_add_f32_e32 v113, 1.0, v113
	v_add_f32_e32 v106, 1.0, v106
	v_add_f32_e32 v107, 1.0, v107
	v_add_f32_e32 v108, 1.0, v108
	v_add_f32_e32 v109, 1.0, v109
	v_add_f32_e32 v102, 1.0, v102
	v_add_f32_e32 v103, 1.0, v103
	v_add_f32_e32 v104, 1.0, v104
	v_add_f32_e32 v105, 1.0, v105
	v_add_f32_e32 v98, 1.0, v98
	v_add_f32_e32 v99, 1.0, v99
	v_add_f32_e32 v100, 1.0, v100
	v_add_f32_e32 v101, 1.0, v101
	v_rcp_f32_e32 v110, v110
	v_rcp_f32_e32 v111, v111
	v_rcp_f32_e32 v112, v112
	v_rcp_f32_e32 v113, v113
	v_rcp_f32_e32 v106, v106
	v_rcp_f32_e32 v107, v107
	v_rcp_f32_e32 v108, v108
	v_rcp_f32_e32 v109, v109
	v_rcp_f32_e32 v102, v102
	v_rcp_f32_e32 v103, v103
	v_rcp_f32_e32 v104, v104
	v_rcp_f32_e32 v105, v105
	v_rcp_f32_e32 v98, v98
	v_rcp_f32_e32 v99, v99
	v_rcp_f32_e32 v100, v100
	v_rcp_f32_e32 v101, v101
	s_waitcnt vmcnt(16)
	v_lshlrev_b32_e32 v150, 16, v180
	v_and_b32_e32 v151, 0xffff0000, v180
	v_lshlrev_b32_e32 v152, 16, v181
	v_and_b32_e32 v153, 0xffff0000, v181
	v_lshlrev_b32_e32 v154, 16, v182
	v_and_b32_e32 v155, 0xffff0000, v182
	v_lshlrev_b32_e32 v156, 16, v183
	v_and_b32_e32 v157, 0xffff0000, v183
	v_pk_fma_f32 v[188:189], v[110:111], v[150:151], v[188:189]
	v_pk_fma_f32 v[190:191], v[112:113], v[152:153], v[190:191]
	v_pk_fma_f32 v[192:193], v[106:107], v[154:155], v[192:193]
	v_pk_fma_f32 v[194:195], v[108:109], v[156:157], v[194:195]
	v_lshlrev_b32_e32 v150, 16, v184
	v_and_b32_e32 v151, 0xffff0000, v184
	v_lshlrev_b32_e32 v152, 16, v185
	v_and_b32_e32 v153, 0xffff0000, v185
	v_lshlrev_b32_e32 v154, 16, v186
	v_and_b32_e32 v155, 0xffff0000, v186
	v_lshlrev_b32_e32 v156, 16, v187
	v_and_b32_e32 v157, 0xffff0000, v187
	v_pk_fma_f32 v[200:201], v[102:103], v[150:151], v[200:201]
	v_pk_fma_f32 v[202:203], v[104:105], v[152:153], v[202:203]
	v_pk_fma_f32 v[204:205], v[98:99], v[154:155], v[204:205]
	v_pk_fma_f32 v[206:207], v[100:101], v[156:157], v[206:207]
	v_add_u32_e32 v145, 0x10000, v144
	global_store_dwordx4 v145, v[188:191], s[8:9]
	global_store_dwordx4 v145, v[192:195], s[8:9] offset:16
	global_store_dwordx4 v145, v[200:203], s[8:9] offset:512
	global_store_dwordx4 v145, v[204:207], s[8:9] offset:528
	v_mul_f32_e32 v220, v189, v189
	v_fmac_f32_e32 v220, v188, v188
	v_mul_f32_e32 v221, v191, v191
	v_fmac_f32_e32 v221, v190, v190
	v_add_f32_e32 v221, v220, v221
	v_mul_f32_e32 v220, v193, v193
	v_fmac_f32_e32 v220, v192, v192
	v_add_f32_e32 v221, v221, v220
	v_mul_f32_e32 v220, v195, v195
	v_fmac_f32_e32 v220, v194, v194
	v_add_f32_e32 v199, v220, v221
	v_mul_f32_e32 v220, v201, v201
	v_fmac_f32_e32 v220, v200, v200
	v_mul_f32_e32 v221, v203, v203
	v_fmac_f32_e32 v221, v202, v202
	v_add_f32_e32 v221, v220, v221
	v_mul_f32_e32 v220, v205, v205
	v_fmac_f32_e32 v220, v204, v204
	v_add_f32_e32 v221, v221, v220
	v_mul_f32_e32 v220, v207, v207
	v_fmac_f32_e32 v220, v206, v206
	v_add_f32_e32 v221, v220, v221
	v_add_f32_e32 v110, v199, v221
	v_xor_b32_e32 v220, 16, v226
	v_lshlrev_b32_e32 v220, 2, v220
	ds_bpermute_b32 v111, v220, v110
	v_add_u32_e32 v145, 0x80000, v144
	v_lshrrev_b32_e32 v198, 1, v145
	global_load_dwordx4 v[180:183], v198, s[10:11]
	global_load_dwordx4 v[184:187], v198, s[10:11] offset:256
	global_load_dwordx4 v[188:191], v145, s[8:9]
	global_load_dwordx4 v[192:195], v145, s[8:9] offset:16
	global_load_dwordx4 v[200:203], v145, s[8:9] offset:512
	global_load_dwordx4 v[204:207], v145, s[8:9] offset:528
	v_lshl_add_u32 v199, v146, 2, s38
	ds_read_b32 v159, v199 offset:128
	s_waitcnt lgkmcnt(0)
; __device__ __forceinline__ u32x4 pack8(f32x4 a, f32x4 b) { u32x4 w; w.x = cvt_pk_bf16(a[0], a[1]); w.y = cvt_pk_bf16(a[2], a[3]); w.z = cvt_pk_bf16(b[0], b[1]); w.w = cvt_pk_bf16(b[2], b[3]); return w; }
; __device__ __forceinline__ void unpack8(u32x4 w, f32x4& a, f32x4& b) { a = (f32x4){bflo(w.x), bfhi(w.x), bflo(w.y), bfhi(w.y)}; b = (f32x4){bflo(w.z), bfhi(w.z), bflo(w.w), bfhi(w.w)}; }
; __device__ __forceinline__ float sigmoidf_(float x) { return __builtin_amdgcn_rcpf(1.f + __builtin_amdgcn_exp2f(-1.4426950408889634f * x)); }
; __device__ __forceinline__ float xhalf_sum(float v) { const auto r_ = __builtin_amdgcn_permlane32_swap(__float_as_uint(v), __float_as_uint(v), false, false); return __uint_as_float(r_[0]) + __uint_as_float(r_[1]); }
; #define EPI_ROWS_END if (m & 1) asm volatile("" ::: "memory"); }
;     __device__ __forceinline__ void operator()(AccRef acc, const Unit& u, int wr, int wc, int fr, int fq) const {
;         const int col0 = u.pn * 256 + wc * 32 + 8 * fq;
;         EPI_ROWS_BEGIN
;             float r = 1.f; if (MODE == 1) r = RSL(u, row);
;             float ss = 0.f;
; #pragma unroll
;             for (int bj = 0; bj < 2; ++bj) {
;                 const size_t off = (size_t)row * 1024 + col0 + bj * 128;
;                 f32x4 a0 = acc[ai][bj][m][0], a1 = acc[ai][bj][m][1];
;                 if (MODE == 1) { f32x4 t0, t1; unpack8(*(const u32x4*)(tp + off), t0, t1);
; #pragma unroll
;                     for (int e = 0; e < 4; ++e) { a0[e] = sigmoidf_(a0[e] * r) * t0[e]; a1[e] = sigmoidf_(a1[e] * r) * t1[e]; } }
;                 const f32x4 n0 = *(const f32x4*)(xold + off) + a0, n1 = *(const f32x4*)(xold + off + 4) + a1;
;                 *(f32x4*)(xf + off) = n0; *(f32x4*)(xf + off + 4) = n1;
;                 if (MODE == 0) *(u32x4*)(xb + off) = pack8(n0, n1);
;                 ss += (n0[0] * n0[0] + n0[1] * n0[1]) + (n0[2] * n0[2] + n0[3] * n0[3]) + (n1[0] * n1[0] + n1[1] * n1[1]) + (n1[2] * n1[2] + n1[3] * n1[3]);
;             }
;             ss += __shfl_xor(ss, 16); ss = xhalf_sum(ss);
;             if (fq == 0) ssq_out[(size_t)row * 16 + u.pn * 4 + wc] = ss;
;         EPI_ROWS_END
	v_mul_f32_e32 v94, v94, v159
	v_mul_f32_e32 v95, v95, v159
	v_mul_f32_e32 v96, v96, v159
	v_mul_f32_e32 v97, v97, v159
	v_mul_f32_e32 v90, v90, v159
	v_mul_f32_e32 v91, v91, v159
	v_mul_f32_e32 v92, v92, v159
	v_mul_f32_e32 v93, v93, v159
	v_mul_f32_e32 v86, v86, v159
	v_mul_f32_e32 v87, v87, v159
	v_mul_f32_e32 v88, v88, v159
	v_mul_f32_e32 v89, v89, v159
	v_mul_f32_e32 v82, v82, v159
	v_mul_f32_e32 v83, v83, v159
	v_mul_f32_e32 v84, v84, v159
	v_mul_f32_e32 v85, v85, v159
	v_mul_f32_e32 v94, 0xbfb8aa3b, v94
	v_mul_f32_e32 v95, 0xbfb8aa3b, v95
	v_mul_f32_e32 v96, 0xbfb8aa3b, v96
	v_mul_f32_e32 v97, 0xbfb8aa3b, v97
	v_mul_f32_e32 v90, 0xbfb8aa3b, v90
	v_mul_f32_e32 v91, 0xbfb8aa3b, v91
	v_mul_f32_e32 v92, 0xbfb8aa3b, v92
	v_mul_f32_e32 v93, 0xbfb8aa3b, v93
	v_mul_f32_e32 v86, 0xbfb8aa3b, v86
	v_mul_f32_e32 v87, 0xbfb8aa3b, v87
	v_mul_f32_e32 v88, 0xbfb8aa3b, v88
	v_mul_f32_e32 v89, 0xbfb8aa3b, v89
	v_mul_f32_e32 v82, 0xbfb8aa3b, v82
	v_mul_f32_e32 v83, 0xbfb8aa3b, v83
	v_mul_f32_e32 v84, 0xbfb8aa3b, v84
	v_mul_f32_e32 v85, 0xbfb8aa3b, v85
	v_exp_f32_e32 v94, v94
	v_exp_f32_e32 v95, v95
	v_exp_f32_e32 v96, v96
	v_exp_f32_e32 v97, v97
	v_exp_f32_e32 v90, v90
	v_exp_f32_e32 v91, v91
	v_exp_f32_e32 v92, v92
	v_exp_f32_e32 v93, v93
	v_exp_f32_e32 v86, v86
	v_exp_f32_e32 v87, v87
	v_exp_f32_e32 v88, v88
	v_exp_f32_e32 v89, v89
	v_exp_f32_e32 v82, v82
	v_exp_f32_e32 v83, v83
	v_exp_f32_e32 v84, v84
	v_exp_f32_e32 v85, v85
	v_add_f32_e32 v94, 1.0, v94
	v_add_f32_e32 v95, 1.0, v95
	v_add_f32_e32 v96, 1.0, v96
	v_add_f32_e32 v97, 1.0, v97
	v_add_f32_e32 v90, 1.0, v90
	v_add_f32_e32 v91, 1.0, v91
	v_add_f32_e32 v92, 1.0, v92
	v_add_f32_e32 v93, 1.0, v93
	v_add_f32_e32 v86, 1.0, v86
	v_add_f32_e32 v87, 1.0, v87
	v_add_f32_e32 v88, 1.0, v88
	v_add_f32_e32 v89, 1.0, v89
	v_add_f32_e32 v82, 1.0, v82
	v_add_f32_e32 v83, 1.0, v83
	v_add_f32_e32 v84, 1.0, v84
	v_add_f32_e32 v85, 1.0, v85
	v_rcp_f32_e32 v94, v94
	v_rcp_f32_e32 v95, v95
	v_rcp_f32_e32 v96, v96
	v_rcp_f32_e32 v97, v97
	v_rcp_f32_e32 v90, v90
	v_rcp_f32_e32 v91, v91
	v_rcp_f32_e32 v92, v92
	v_rcp_f32_e32 v93, v93
	v_rcp_f32_e32 v86, v86
	v_rcp_f32_e32 v87, v87
	v_rcp_f32_e32 v88, v88
	v_rcp_f32_e32 v89, v89
	v_rcp_f32_e32 v82, v82
	v_rcp_f32_e32 v83, v83
	v_rcp_f32_e32 v84, v84
	v_rcp_f32_e32 v85, v85
	s_waitcnt vmcnt(20)
	v_lshlrev_b32_e32 v150, 16, v208
	v_and_b32_e32 v151, 0xffff0000, v208
	v_lshlrev_b32_e32 v152, 16, v209
	v_and_b32_e32 v153, 0xffff0000, v209
	v_lshlrev_b32_e32 v154, 16, v210
	v_and_b32_e32 v155, 0xffff0000, v210
	v_lshlrev_b32_e32 v156, 16, v211
	v_and_b32_e32 v157, 0xffff0000, v211
	v_pk_fma_f32 v[216:217], v[94:95], v[150:151], v[216:217]
	v_pk_fma_f32 v[218:219], v[96:97], v[152:153], v[218:219]
	v_pk_fma_f32 v[236:237], v[90:91], v[154:155], v[236:237]
	v_pk_fma_f32 v[238:239], v[92:93], v[156:157], v[238:239]
	v_lshlrev_b32_e32 v150, 16, v212
	v_and_b32_e32 v151, 0xffff0000, v212
	v_lshlrev_b32_e32 v152, 16, v213
	v_and_b32_e32 v153, 0xffff0000, v213
	v_lshlrev_b32_e32 v154, 16, v214
	v_and_b32_e32 v155, 0xffff0000, v214
	v_lshlrev_b32_e32 v156, 16, v215
	v_and_b32_e32 v157, 0xffff0000, v215
	v_pk_fma_f32 v[240:241], v[86:87], v[150:151], v[240:241]
	v_pk_fma_f32 v[242:243], v[88:89], v[152:153], v[242:243]
	v_pk_fma_f32 v[244:245], v[82:83], v[154:155], v[244:245]
	v_pk_fma_f32 v[246:247], v[84:85], v[156:157], v[246:247]
	v_add_u32_e32 v145, 0x20000, v144
	global_store_dwordx4 v145, v[216:219], s[8:9]
	global_store_dwordx4 v145, v[236:239], s[8:9] offset:16
	global_store_dwordx4 v145, v[240:243], s[8:9] offset:512
	global_store_dwordx4 v145, v[244:247], s[8:9] offset:528
	v_mul_f32_e32 v220, v217, v217
	v_fmac_f32_e32 v220, v216, v216
	v_mul_f32_e32 v221, v219, v219
	v_fmac_f32_e32 v221, v218, v218
	v_add_f32_e32 v221, v220, v221
	v_mul_f32_e32 v220, v237, v237
	v_fmac_f32_e32 v220, v236, v236
	v_add_f32_e32 v221, v221, v220
	v_mul_f32_e32 v220, v239, v239
	v_fmac_f32_e32 v220, v238, v238
	v_add_f32_e32 v199, v220, v221
	v_mul_f32_e32 v220, v241, v241
	v_fmac_f32_e32 v220, v240, v240
	v_mul_f32_e32 v221, v243, v243
	v_fmac_f32_e32 v221, v242, v242
	v_add_f32_e32 v221, v220, v221
	v_mul_f32_e32 v220, v245, v245
	v_fmac_f32_e32 v220, v244, v244
	v_add_f32_e32 v221, v221, v220
	v_mul_f32_e32 v220, v247, v247
	v_fmac_f32_e32 v220, v246, v246
	v_add_f32_e32 v221, v220, v221
	v_add_f32_e32 v94, v199, v221
	v_xor_b32_e32 v220, 16, v226
	v_lshlrev_b32_e32 v220, 2, v220
	ds_bpermute_b32 v95, v220, v94
	v_add_u32_e32 v145, 0x90000, v144
	v_lshrrev_b32_e32 v198, 1, v145
	global_load_dwordx4 v[208:211], v198, s[10:11]
	global_load_dwordx4 v[212:215], v198, s[10:11] offset:256
	global_load_dwordx4 v[216:219], v145, s[8:9]
	global_load_dwordx4 v[236:239], v145, s[8:9] offset:16
	global_load_dwordx4 v[240:243], v145, s[8:9] offset:512
	global_load_dwordx4 v[244:247], v145, s[8:9] offset:528
	v_lshl_add_u32 v199, v146, 2, s38
	ds_read_b32 v159, v199 offset:192
	s_waitcnt lgkmcnt(0)
; __device__ __forceinline__ u32x4 pack8(f32x4 a, f32x4 b) { u32x4 w; w.x = cvt_pk_bf16(a[0], a[1]); w.y = cvt_pk_bf16(a[2], a[3]); w.z = cvt_pk_bf16(b[0], b[1]); w.w = cvt_pk_bf16(b[2], b[3]); return w; }
; __device__ __forceinline__ void unpack8(u32x4 w, f32x4& a, f32x4& b) { a = (f32x4){bflo(w.x), bfhi(w.x), bflo(w.y), bfhi(w.y)}; b = (f32x4){bflo(w.z), bfhi(w.z), bflo(w.w), bfhi(w.w)}; }
; __device__ __forceinline__ float sigmoidf_(float x) { return __builtin_amdgcn_rcpf(1.f + __builtin_amdgcn_exp2f(-1.4426950408889634f * x)); }
; __device__ __forceinline__ float xhalf_sum(float v) { const auto r_ = __builtin_amdgcn_permlane32_swap(__float_as_uint(v), __float_as_uint(v), false, false); return __uint_as_float(r_[0]) + __uint_as_float(r_[1]); }
; #define EPI_ROWS_END if (m & 1) asm volatile("" ::: "memory"); }
;     __device__ __forceinline__ void operator()(AccRef acc, const Unit& u, int wr, int wc, int fr, int fq) const {
;         const int col0 = u.pn * 256 + wc * 32 + 8 * fq;
;         EPI_ROWS_BEGIN
;             float r = 1.f; if (MODE == 1) r = RSL(u, row);
;             float ss = 0.f;
; #pragma unroll
;             for (int bj = 0; bj < 2; ++bj) {
;                 const size_t off = (size_t)row * 1024 + col0 + bj * 128;
;                 f32x4 a0 = acc[ai][bj][m][0], a1 = acc[ai][bj][m][1];
;                 if (MODE == 1) { f32x4 t0, t1; unpack8(*(const u32x4*)(tp + off), t0, t1);
; #pragma unroll
;                     for (int e = 0; e < 4; ++e) { a0[e] = sigmoidf_(a0[e] * r) * t0[e]; a1[e] = sigmoidf_(a1[e] * r) * t1[e]; } }
;                 const f32x4 n0 = *(const f32x4*)(xold + off) + a0, n1 = *(const f32x4*)(xold + off + 4) + a1;
;                 *(f32x4*)(xf + off) = n0; *(f32x4*)(xf + off + 4) = n1;
;                 if (MODE == 0) *(u32x4*)(xb + off) = pack8(n0, n1);
;                 ss += (n0[0] * n0[0] + n0[1] * n0[1]) + (n0[2] * n0[2] + n0[3] * n0[3]) + (n1[0] * n1[0] + n1[1] * n1[1]) + (n1[2] * n1[2] + n1[3] * n1[3]);
;             }
;             ss += __shfl_xor(ss, 16); ss = xhalf_sum(ss);
;             if (fq == 0) ssq_out[(size_t)row * 16 + u.pn * 4 + wc] = ss;
;         EPI_ROWS_END
	v_mul_f32_e32 v78, v78, v159
	v_mul_f32_e32 v79, v79, v159
	v_mul_f32_e32 v80, v80, v159
	v_mul_f32_e32 v81, v81, v159
	v_mul_f32_e32 v74, v74, v159
	v_mul_f32_e32 v75, v75, v159
	v_mul_f32_e32 v76, v76, v159
	v_mul_f32_e32 v77, v77, v159
	v_mul_f32_e32 v70, v70, v159
	v_mul_f32_e32 v71, v71, v159
	v_mul_f32_e32 v72, v72, v159
	v_mul_f32_e32 v73, v73, v159
	v_mul_f32_e32 v66, v66, v159
	v_mul_f32_e32 v67, v67, v159
	v_mul_f32_e32 v68, v68, v159
	v_mul_f32_e32 v69, v69, v159
	v_mul_f32_e32 v78, 0xbfb8aa3b, v78
	v_mul_f32_e32 v79, 0xbfb8aa3b, v79
	v_mul_f32_e32 v80, 0xbfb8aa3b, v80
	v_mul_f32_e32 v81, 0xbfb8aa3b, v81
	v_mul_f32_e32 v74, 0xbfb8aa3b, v74
	v_mul_f32_e32 v75, 0xbfb8aa3b, v75
	v_mul_f32_e32 v76, 0xbfb8aa3b, v76
	v_mul_f32_e32 v77, 0xbfb8aa3b, v77
	v_mul_f32_e32 v70, 0xbfb8aa3b, v70
	v_mul_f32_e32 v71, 0xbfb8aa3b, v71
	v_mul_f32_e32 v72, 0xbfb8aa3b, v72
	v_mul_f32_e32 v73, 0xbfb8aa3b, v73
	v_mul_f32_e32 v66, 0xbfb8aa3b, v66
	v_mul_f32_e32 v67, 0xbfb8aa3b, v67
	v_mul_f32_e32 v68, 0xbfb8aa3b, v68
	v_mul_f32_e32 v69, 0xbfb8aa3b, v69
	v_exp_f32_e32 v78, v78
	v_exp_f32_e32 v79, v79
	v_exp_f32_e32 v80, v80
	v_exp_f32_e32 v81, v81
	v_exp_f32_e32 v74, v74
	v_exp_f32_e32 v75, v75
	v_exp_f32_e32 v76, v76
	v_exp_f32_e32 v77, v77
	v_exp_f32_e32 v70, v70
	v_exp_f32_e32 v71, v71
	v_exp_f32_e32 v72, v72
	v_exp_f32_e32 v73, v73
	v_exp_f32_e32 v66, v66
	v_exp_f32_e32 v67, v67
	v_exp_f32_e32 v68, v68
	v_exp_f32_e32 v69, v69
	v_add_f32_e32 v78, 1.0, v78
	v_add_f32_e32 v79, 1.0, v79
	v_add_f32_e32 v80, 1.0, v80
	v_add_f32_e32 v81, 1.0, v81
	v_add_f32_e32 v74, 1.0, v74
	v_add_f32_e32 v75, 1.0, v75
	v_add_f32_e32 v76, 1.0, v76
	v_add_f32_e32 v77, 1.0, v77
	v_add_f32_e32 v70, 1.0, v70
	v_add_f32_e32 v71, 1.0, v71
	v_add_f32_e32 v72, 1.0, v72
	v_add_f32_e32 v73, 1.0, v73
	v_add_f32_e32 v66, 1.0, v66
	v_add_f32_e32 v67, 1.0, v67
	v_add_f32_e32 v68, 1.0, v68
	v_add_f32_e32 v69, 1.0, v69
	v_rcp_f32_e32 v78, v78
	v_rcp_f32_e32 v79, v79
	v_rcp_f32_e32 v80, v80
	v_rcp_f32_e32 v81, v81
	v_rcp_f32_e32 v74, v74
	v_rcp_f32_e32 v75, v75
	v_rcp_f32_e32 v76, v76
	v_rcp_f32_e32 v77, v77
	v_rcp_f32_e32 v70, v70
	v_rcp_f32_e32 v71, v71
	v_rcp_f32_e32 v72, v72
	v_rcp_f32_e32 v73, v73
	v_rcp_f32_e32 v66, v66
	v_rcp_f32_e32 v67, v67
	v_rcp_f32_e32 v68, v68
	v_rcp_f32_e32 v69, v69
	s_waitcnt vmcnt(20)
	v_lshlrev_b32_e32 v150, 16, v140
	v_and_b32_e32 v151, 0xffff0000, v140
	v_lshlrev_b32_e32 v152, 16, v141
	v_and_b32_e32 v153, 0xffff0000, v141
	v_lshlrev_b32_e32 v154, 16, v142
	v_and_b32_e32 v155, 0xffff0000, v142
	v_lshlrev_b32_e32 v156, 16, v143
	v_and_b32_e32 v157, 0xffff0000, v143
	v_pk_fma_f32 v[164:165], v[78:79], v[150:151], v[164:165]
	v_pk_fma_f32 v[166:167], v[80:81], v[152:153], v[166:167]
	v_pk_fma_f32 v[168:169], v[74:75], v[154:155], v[168:169]
	v_pk_fma_f32 v[170:171], v[76:77], v[156:157], v[170:171]
	v_lshlrev_b32_e32 v150, 16, v160
	v_and_b32_e32 v151, 0xffff0000, v160
	v_lshlrev_b32_e32 v152, 16, v161
	v_and_b32_e32 v153, 0xffff0000, v161
	v_lshlrev_b32_e32 v154, 16, v162
	v_and_b32_e32 v155, 0xffff0000, v162
	v_lshlrev_b32_e32 v156, 16, v163
	v_and_b32_e32 v157, 0xffff0000, v163
	v_pk_fma_f32 v[172:173], v[70:71], v[150:151], v[172:173]
	v_pk_fma_f32 v[174:175], v[72:73], v[152:153], v[174:175]
	v_pk_fma_f32 v[176:177], v[66:67], v[154:155], v[176:177]
	v_pk_fma_f32 v[178:179], v[68:69], v[156:157], v[178:179]
	v_add_u32_e32 v145, 0x30000, v144
	global_store_dwordx4 v145, v[164:167], s[8:9]
	global_store_dwordx4 v145, v[168:171], s[8:9] offset:16
	global_store_dwordx4 v145, v[172:175], s[8:9] offset:512
	global_store_dwordx4 v145, v[176:179], s[8:9] offset:528
	v_mul_f32_e32 v220, v165, v165
	v_fmac_f32_e32 v220, v164, v164
	v_mul_f32_e32 v221, v167, v167
	v_fmac_f32_e32 v221, v166, v166
	v_add_f32_e32 v221, v220, v221
	v_mul_f32_e32 v220, v169, v169
	v_fmac_f32_e32 v220, v168, v168
	v_add_f32_e32 v221, v221, v220
	v_mul_f32_e32 v220, v171, v171
	v_fmac_f32_e32 v220, v170, v170
	v_add_f32_e32 v199, v220, v221
	v_mul_f32_e32 v220, v173, v173
	v_fmac_f32_e32 v220, v172, v172
	v_mul_f32_e32 v221, v175, v175
	v_fmac_f32_e32 v221, v174, v174
	v_add_f32_e32 v221, v220, v221
	v_mul_f32_e32 v220, v177, v177
	v_fmac_f32_e32 v220, v176, v176
	v_add_f32_e32 v221, v221, v220
	v_mul_f32_e32 v220, v179, v179
	v_fmac_f32_e32 v220, v178, v178
	v_add_f32_e32 v221, v220, v221
	v_add_f32_e32 v78, v199, v221
	v_xor_b32_e32 v220, 16, v226
	v_lshlrev_b32_e32 v220, 2, v220
	ds_bpermute_b32 v79, v220, v78
	v_add_u32_e32 v145, 0xa0000, v144
	v_lshrrev_b32_e32 v198, 1, v145
	global_load_dwordx4 v[140:143], v198, s[10:11]
	global_load_dwordx4 v[160:163], v198, s[10:11] offset:256
	global_load_dwordx4 v[164:167], v145, s[8:9]
	global_load_dwordx4 v[168:171], v145, s[8:9] offset:16
	global_load_dwordx4 v[172:175], v145, s[8:9] offset:512
	global_load_dwordx4 v[176:179], v145, s[8:9] offset:528
	v_lshl_add_u32 v199, v146, 2, s38
	ds_read_b32 v159, v199 offset:512
	s_waitcnt lgkmcnt(0)
; __device__ __forceinline__ u32x4 pack8(f32x4 a, f32x4 b) { u32x4 w; w.x = cvt_pk_bf16(a[0], a[1]); w.y = cvt_pk_bf16(a[2], a[3]); w.z = cvt_pk_bf16(b[0], b[1]); w.w = cvt_pk_bf16(b[2], b[3]); return w; }
; __device__ __forceinline__ void unpack8(u32x4 w, f32x4& a, f32x4& b) { a = (f32x4){bflo(w.x), bfhi(w.x), bflo(w.y), bfhi(w.y)}; b = (f32x4){bflo(w.z), bfhi(w.z), bflo(w.w), bfhi(w.w)}; }
; __device__ __forceinline__ float sigmoidf_(float x) { return __builtin_amdgcn_rcpf(1.f + __builtin_amdgcn_exp2f(-1.4426950408889634f * x)); }
; __device__ __forceinline__ float xhalf_sum(float v) { const auto r_ = __builtin_amdgcn_permlane32_swap(__float_as_uint(v), __float_as_uint(v), false, false); return __uint_as_float(r_[0]) + __uint_as_float(r_[1]); }
; #define EPI_ROWS_END if (m & 1) asm volatile("" ::: "memory"); }
;     __device__ __forceinline__ void operator()(AccRef acc, const Unit& u, int wr, int wc, int fr, int fq) const {
;         const int col0 = u.pn * 256 + wc * 32 + 8 * fq;
;         EPI_ROWS_BEGIN
;             float r = 1.f; if (MODE == 1) r = RSL(u, row);
;             float ss = 0.f;
; #pragma unroll
;             for (int bj = 0; bj < 2; ++bj) {
;                 const size_t off = (size_t)row * 1024 + col0 + bj * 128;
;                 f32x4 a0 = acc[ai][bj][m][0], a1 = acc[ai][bj][m][1];
;                 if (MODE == 1) { f32x4 t0, t1; unpack8(*(const u32x4*)(tp + off), t0, t1);
; #pragma unroll
;                     for (int e = 0; e < 4; ++e) { a0[e] = sigmoidf_(a0[e] * r) * t0[e]; a1[e] = sigmoidf_(a1[e] * r) * t1[e]; } }
;                 const f32x4 n0 = *(const f32x4*)(xold + off) + a0, n1 = *(const f32x4*)(xold + off + 4) + a1;
;                 *(f32x4*)(xf + off) = n0; *(f32x4*)(xf + off + 4) = n1;
;                 if (MODE == 0) *(u32x4*)(xb + off) = pack8(n0, n1);
;                 ss += (n0[0] * n0[0] + n0[1] * n0[1]) + (n0[2] * n0[2] + n0[3] * n0[3]) + (n1[0] * n1[0] + n1[1] * n1[1]) + (n1[2] * n1[2] + n1[3] * n1[3]);
;             }
;             ss += __shfl_xor(ss, 16); ss = xhalf_sum(ss);
;             if (fq == 0) ssq_out[(size_t)row * 16 + u.pn * 4 + wc] = ss;
;         EPI_ROWS_END
	v_mul_f32_e32 v62, v62, v159
	v_mul_f32_e32 v63, v63, v159
	v_mul_f32_e32 v64, v64, v159
	v_mul_f32_e32 v65, v65, v159
	v_mul_f32_e32 v58, v58, v159
	v_mul_f32_e32 v59, v59, v159
	v_mul_f32_e32 v60, v60, v159
	v_mul_f32_e32 v61, v61, v159
	v_mul_f32_e32 v54, v54, v159
	v_mul_f32_e32 v55, v55, v159
	v_mul_f32_e32 v56, v56, v159
	v_mul_f32_e32 v57, v57, v159
	v_mul_f32_e32 v50, v50, v159
	v_mul_f32_e32 v51, v51, v159
	v_mul_f32_e32 v52, v52, v159
	v_mul_f32_e32 v53, v53, v159
	v_mul_f32_e32 v62, 0xbfb8aa3b, v62
	v_mul_f32_e32 v63, 0xbfb8aa3b, v63
	v_mul_f32_e32 v64, 0xbfb8aa3b, v64
	v_mul_f32_e32 v65, 0xbfb8aa3b, v65
	v_mul_f32_e32 v58, 0xbfb8aa3b, v58
	v_mul_f32_e32 v59, 0xbfb8aa3b, v59
	v_mul_f32_e32 v60, 0xbfb8aa3b, v60
	v_mul_f32_e32 v61, 0xbfb8aa3b, v61
	v_mul_f32_e32 v54, 0xbfb8aa3b, v54
	v_mul_f32_e32 v55, 0xbfb8aa3b, v55
	v_mul_f32_e32 v56, 0xbfb8aa3b, v56
	v_mul_f32_e32 v57, 0xbfb8aa3b, v57
	v_mul_f32_e32 v50, 0xbfb8aa3b, v50
	v_mul_f32_e32 v51, 0xbfb8aa3b, v51
	v_mul_f32_e32 v52, 0xbfb8aa3b, v52
	v_mul_f32_e32 v53, 0xbfb8aa3b, v53
	v_exp_f32_e32 v62, v62
	v_exp_f32_e32 v63, v63
	v_exp_f32_e32 v64, v64
	v_exp_f32_e32 v65, v65
	v_exp_f32_e32 v58, v58
	v_exp_f32_e32 v59, v59
	v_exp_f32_e32 v60, v60
	v_exp_f32_e32 v61, v61
	v_exp_f32_e32 v54, v54
	v_exp_f32_e32 v55, v55
	v_exp_f32_e32 v56, v56
	v_exp_f32_e32 v57, v57
	v_exp_f32_e32 v50, v50
	v_exp_f32_e32 v51, v51
	v_exp_f32_e32 v52, v52
	v_exp_f32_e32 v53, v53
	v_add_f32_e32 v62, 1.0, v62
	v_add_f32_e32 v63, 1.0, v63
	v_add_f32_e32 v64, 1.0, v64
	v_add_f32_e32 v65, 1.0, v65
	v_add_f32_e32 v58, 1.0, v58
	v_add_f32_e32 v59, 1.0, v59
	v_add_f32_e32 v60, 1.0, v60
	v_add_f32_e32 v61, 1.0, v61
	v_add_f32_e32 v54, 1.0, v54
	v_add_f32_e32 v55, 1.0, v55
	v_add_f32_e32 v56, 1.0, v56
	v_add_f32_e32 v57, 1.0, v57
	v_add_f32_e32 v50, 1.0, v50
	v_add_f32_e32 v51, 1.0, v51
	v_add_f32_e32 v52, 1.0, v52
	v_add_f32_e32 v53, 1.0, v53
	v_rcp_f32_e32 v62, v62
	v_rcp_f32_e32 v63, v63
	v_rcp_f32_e32 v64, v64
	v_rcp_f32_e32 v65, v65
	v_rcp_f32_e32 v58, v58
	v_rcp_f32_e32 v59, v59
	v_rcp_f32_e32 v60, v60
	v_rcp_f32_e32 v61, v61
	v_rcp_f32_e32 v54, v54
	v_rcp_f32_e32 v55, v55
	v_rcp_f32_e32 v56, v56
	v_rcp_f32_e32 v57, v57
	v_rcp_f32_e32 v50, v50
	v_rcp_f32_e32 v51, v51
	v_rcp_f32_e32 v52, v52
	v_rcp_f32_e32 v53, v53
	s_waitcnt vmcnt(20)
	v_lshlrev_b32_e32 v150, 16, v180
	v_and_b32_e32 v151, 0xffff0000, v180
	v_lshlrev_b32_e32 v152, 16, v181
	v_and_b32_e32 v153, 0xffff0000, v181
	v_lshlrev_b32_e32 v154, 16, v182
	v_and_b32_e32 v155, 0xffff0000, v182
	v_lshlrev_b32_e32 v156, 16, v183
	v_and_b32_e32 v157, 0xffff0000, v183
	v_pk_fma_f32 v[188:189], v[62:63], v[150:151], v[188:189]
	v_pk_fma_f32 v[190:191], v[64:65], v[152:153], v[190:191]
	v_pk_fma_f32 v[192:193], v[58:59], v[154:155], v[192:193]
	v_pk_fma_f32 v[194:195], v[60:61], v[156:157], v[194:195]
	v_lshlrev_b32_e32 v150, 16, v184
	v_and_b32_e32 v151, 0xffff0000, v184
	v_lshlrev_b32_e32 v152, 16, v185
	v_and_b32_e32 v153, 0xffff0000, v185
	v_lshlrev_b32_e32 v154, 16, v186
	v_and_b32_e32 v155, 0xffff0000, v186
	v_lshlrev_b32_e32 v156, 16, v187
	v_and_b32_e32 v157, 0xffff0000, v187
	v_pk_fma_f32 v[200:201], v[54:55], v[150:151], v[200:201]
	v_pk_fma_f32 v[202:203], v[56:57], v[152:153], v[202:203]
	v_pk_fma_f32 v[204:205], v[50:51], v[154:155], v[204:205]
	v_pk_fma_f32 v[206:207], v[52:53], v[156:157], v[206:207]
	v_add_u32_e32 v145, 0x80000, v144
	global_store_dwordx4 v145, v[188:191], s[8:9]
	global_store_dwordx4 v145, v[192:195], s[8:9] offset:16
	global_store_dwordx4 v145, v[200:203], s[8:9] offset:512
	global_store_dwordx4 v145, v[204:207], s[8:9] offset:528
	v_mul_f32_e32 v220, v189, v189
	v_fmac_f32_e32 v220, v188, v188
	v_mul_f32_e32 v221, v191, v191
	v_fmac_f32_e32 v221, v190, v190
	v_add_f32_e32 v221, v220, v221
	v_mul_f32_e32 v220, v193, v193
	v_fmac_f32_e32 v220, v192, v192
	v_add_f32_e32 v221, v221, v220
	v_mul_f32_e32 v220, v195, v195
	v_fmac_f32_e32 v220, v194, v194
	v_add_f32_e32 v199, v220, v221
	v_mul_f32_e32 v220, v201, v201
	v_fmac_f32_e32 v220, v200, v200
	v_mul_f32_e32 v221, v203, v203
	v_fmac_f32_e32 v221, v202, v202
	v_add_f32_e32 v221, v220, v221
	v_mul_f32_e32 v220, v205, v205
	v_fmac_f32_e32 v220, v204, v204
	v_add_f32_e32 v221, v221, v220
	v_mul_f32_e32 v220, v207, v207
	v_fmac_f32_e32 v220, v206, v206
	v_add_f32_e32 v221, v220, v221
	v_add_f32_e32 v62, v199, v221
	v_xor_b32_e32 v220, 16, v226
	v_lshlrev_b32_e32 v220, 2, v220
	ds_bpermute_b32 v63, v220, v62
	v_add_u32_e32 v145, 0xb0000, v144
	v_lshrrev_b32_e32 v198, 1, v145
	global_load_dwordx4 v[180:183], v198, s[10:11]
	global_load_dwordx4 v[184:187], v198, s[10:11] offset:256
	global_load_dwordx4 v[188:191], v145, s[8:9]
	global_load_dwordx4 v[192:195], v145, s[8:9] offset:16
	global_load_dwordx4 v[200:203], v145, s[8:9] offset:512
	global_load_dwordx4 v[204:207], v145, s[8:9] offset:528
	v_lshl_add_u32 v199, v146, 2, s38
	ds_read_b32 v159, v199 offset:576
	s_waitcnt lgkmcnt(0)
; __device__ __forceinline__ u32x4 pack8(f32x4 a, f32x4 b) { u32x4 w; w.x = cvt_pk_bf16(a[0], a[1]); w.y = cvt_pk_bf16(a[2], a[3]); w.z = cvt_pk_bf16(b[0], b[1]); w.w = cvt_pk_bf16(b[2], b[3]); return w; }
; __device__ __forceinline__ void unpack8(u32x4 w, f32x4& a, f32x4& b) { a = (f32x4){bflo(w.x), bfhi(w.x), bflo(w.y), bfhi(w.y)}; b = (f32x4){bflo(w.z), bfhi(w.z), bflo(w.w), bfhi(w.w)}; }
; __device__ __forceinline__ float sigmoidf_(float x) { return __builtin_amdgcn_rcpf(1.f + __builtin_amdgcn_exp2f(-1.4426950408889634f * x)); }
; __device__ __forceinline__ float xhalf_sum(float v) { const auto r_ = __builtin_amdgcn_permlane32_swap(__float_as_uint(v), __float_as_uint(v), false, false); return __uint_as_float(r_[0]) + __uint_as_float(r_[1]); }
; #define EPI_ROWS_END if (m & 1) asm volatile("" ::: "memory"); }
;     __device__ __forceinline__ void operator()(AccRef acc, const Unit& u, int wr, int wc, int fr, int fq) const {
;         const int col0 = u.pn * 256 + wc * 32 + 8 * fq;
;         EPI_ROWS_BEGIN
;             float r = 1.f; if (MODE == 1) r = RSL(u, row);
;             float ss = 0.f;
; #pragma unroll
;             for (int bj = 0; bj < 2; ++bj) {
;                 const size_t off = (size_t)row * 1024 + col0 + bj * 128;
;                 f32x4 a0 = acc[ai][bj][m][0], a1 = acc[ai][bj][m][1];
;                 if (MODE == 1) { f32x4 t0, t1; unpack8(*(const u32x4*)(tp + off), t0, t1);
; #pragma unroll
;                     for (int e = 0; e < 4; ++e) { a0[e] = sigmoidf_(a0[e] * r) * t0[e]; a1[e] = sigmoidf_(a1[e] * r) * t1[e]; } }
;                 const f32x4 n0 = *(const f32x4*)(xold + off) + a0, n1 = *(const f32x4*)(xold + off + 4) + a1;
;                 *(f32x4*)(xf + off) = n0; *(f32x4*)(xf + off + 4) = n1;
;                 if (MODE == 0) *(u32x4*)(xb + off) = pack8(n0, n1);
;                 ss += (n0[0] * n0[0] + n0[1] * n0[1]) + (n0[2] * n0[2] + n0[3] * n0[3]) + (n1[0] * n1[0] + n1[1] * n1[1]) + (n1[2] * n1[2] + n1[3] * n1[3]);
;             }
;             ss += __shfl_xor(ss, 16); ss = xhalf_sum(ss);
;             if (fq == 0) ssq_out[(size_t)row * 16 + u.pn * 4 + wc] = ss;
;         EPI_ROWS_END
	v_mul_f32_e32 v46, v46, v159
	v_mul_f32_e32 v47, v47, v159
	v_mul_f32_e32 v48, v48, v159
	v_mul_f32_e32 v49, v49, v159
	v_mul_f32_e32 v42, v42, v159
	v_mul_f32_e32 v43, v43, v159
	v_mul_f32_e32 v44, v44, v159
	v_mul_f32_e32 v45, v45, v159
	v_mul_f32_e32 v38, v38, v159
	v_mul_f32_e32 v39, v39, v159
	v_mul_f32_e32 v40, v40, v159
	v_mul_f32_e32 v41, v41, v159
	v_mul_f32_e32 v34, v34, v159
	v_mul_f32_e32 v35, v35, v159
	v_mul_f32_e32 v36, v36, v159
	v_mul_f32_e32 v37, v37, v159
	v_mul_f32_e32 v46, 0xbfb8aa3b, v46
	v_mul_f32_e32 v47, 0xbfb8aa3b, v47
	v_mul_f32_e32 v48, 0xbfb8aa3b, v48
	v_mul_f32_e32 v49, 0xbfb8aa3b, v49
	v_mul_f32_e32 v42, 0xbfb8aa3b, v42
	v_mul_f32_e32 v43, 0xbfb8aa3b, v43
	v_mul_f32_e32 v44, 0xbfb8aa3b, v44
	v_mul_f32_e32 v45, 0xbfb8aa3b, v45
	v_mul_f32_e32 v38, 0xbfb8aa3b, v38
	v_mul_f32_e32 v39, 0xbfb8aa3b, v39
	v_mul_f32_e32 v40, 0xbfb8aa3b, v40
	v_mul_f32_e32 v41, 0xbfb8aa3b, v41
	v_mul_f32_e32 v34, 0xbfb8aa3b, v34
	v_mul_f32_e32 v35, 0xbfb8aa3b, v35
	v_mul_f32_e32 v36, 0xbfb8aa3b, v36
	v_mul_f32_e32 v37, 0xbfb8aa3b, v37
	v_exp_f32_e32 v46, v46
	v_exp_f32_e32 v47, v47
	v_exp_f32_e32 v48, v48
	v_exp_f32_e32 v49, v49
	v_exp_f32_e32 v42, v42
	v_exp_f32_e32 v43, v43
	v_exp_f32_e32 v44, v44
	v_exp_f32_e32 v45, v45
	v_exp_f32_e32 v38, v38
	v_exp_f32_e32 v39, v39
	v_exp_f32_e32 v40, v40
	v_exp_f32_e32 v41, v41
	v_exp_f32_e32 v34, v34
	v_exp_f32_e32 v35, v35
	v_exp_f32_e32 v36, v36
	v_exp_f32_e32 v37, v37
	v_add_f32_e32 v46, 1.0, v46
	v_add_f32_e32 v47, 1.0, v47
	v_add_f32_e32 v48, 1.0, v48
	v_add_f32_e32 v49, 1.0, v49
	v_add_f32_e32 v42, 1.0, v42
	v_add_f32_e32 v43, 1.0, v43
	v_add_f32_e32 v44, 1.0, v44
	v_add_f32_e32 v45, 1.0, v45
	v_add_f32_e32 v38, 1.0, v38
	v_add_f32_e32 v39, 1.0, v39
	v_add_f32_e32 v40, 1.0, v40
	v_add_f32_e32 v41, 1.0, v41
	v_add_f32_e32 v34, 1.0, v34
	v_add_f32_e32 v35, 1.0, v35
	v_add_f32_e32 v36, 1.0, v36
	v_add_f32_e32 v37, 1.0, v37
	v_rcp_f32_e32 v46, v46
	v_rcp_f32_e32 v47, v47
	v_rcp_f32_e32 v48, v48
	v_rcp_f32_e32 v49, v49
	v_rcp_f32_e32 v42, v42
	v_rcp_f32_e32 v43, v43
	v_rcp_f32_e32 v44, v44
	v_rcp_f32_e32 v45, v45
	v_rcp_f32_e32 v38, v38
	v_rcp_f32_e32 v39, v39
	v_rcp_f32_e32 v40, v40
	v_rcp_f32_e32 v41, v41
	v_rcp_f32_e32 v34, v34
	v_rcp_f32_e32 v35, v35
	v_rcp_f32_e32 v36, v36
	v_rcp_f32_e32 v37, v37
	s_waitcnt vmcnt(20)
	v_lshlrev_b32_e32 v150, 16, v208
	v_and_b32_e32 v151, 0xffff0000, v208
	v_lshlrev_b32_e32 v152, 16, v209
	v_and_b32_e32 v153, 0xffff0000, v209
	v_lshlrev_b32_e32 v154, 16, v210
	v_and_b32_e32 v155, 0xffff0000, v210
	v_lshlrev_b32_e32 v156, 16, v211
	v_and_b32_e32 v157, 0xffff0000, v211
	v_pk_fma_f32 v[216:217], v[46:47], v[150:151], v[216:217]
	v_pk_fma_f32 v[218:219], v[48:49], v[152:153], v[218:219]
	v_pk_fma_f32 v[236:237], v[42:43], v[154:155], v[236:237]
	v_pk_fma_f32 v[238:239], v[44:45], v[156:157], v[238:239]
	v_lshlrev_b32_e32 v150, 16, v212
	v_and_b32_e32 v151, 0xffff0000, v212
	v_lshlrev_b32_e32 v152, 16, v213
	v_and_b32_e32 v153, 0xffff0000, v213
	v_lshlrev_b32_e32 v154, 16, v214
	v_and_b32_e32 v155, 0xffff0000, v214
	v_lshlrev_b32_e32 v156, 16, v215
	v_and_b32_e32 v157, 0xffff0000, v215
	v_pk_fma_f32 v[240:241], v[38:39], v[150:151], v[240:241]
	v_pk_fma_f32 v[242:243], v[40:41], v[152:153], v[242:243]
	v_pk_fma_f32 v[244:245], v[34:35], v[154:155], v[244:245]
	v_pk_fma_f32 v[246:247], v[36:37], v[156:157], v[246:247]
	v_add_u32_e32 v145, 0x90000, v144
	global_store_dwordx4 v145, v[216:219], s[8:9]
	global_store_dwordx4 v145, v[236:239], s[8:9] offset:16
	global_store_dwordx4 v145, v[240:243], s[8:9] offset:512
	global_store_dwordx4 v145, v[244:247], s[8:9] offset:528
	v_mul_f32_e32 v220, v217, v217
	v_fmac_f32_e32 v220, v216, v216
	v_mul_f32_e32 v221, v219, v219
	v_fmac_f32_e32 v221, v218, v218
	v_add_f32_e32 v221, v220, v221
	v_mul_f32_e32 v220, v237, v237
	v_fmac_f32_e32 v220, v236, v236
	v_add_f32_e32 v221, v221, v220
	v_mul_f32_e32 v220, v239, v239
	v_fmac_f32_e32 v220, v238, v238
	v_add_f32_e32 v199, v220, v221
	v_mul_f32_e32 v220, v241, v241
	v_fmac_f32_e32 v220, v240, v240
	v_mul_f32_e32 v221, v243, v243
	v_fmac_f32_e32 v221, v242, v242
	v_add_f32_e32 v221, v220, v221
	v_mul_f32_e32 v220, v245, v245
	v_fmac_f32_e32 v220, v244, v244
	v_add_f32_e32 v221, v221, v220
	v_mul_f32_e32 v220, v247, v247
	v_fmac_f32_e32 v220, v246, v246
	v_add_f32_e32 v221, v220, v221
	v_add_f32_e32 v46, v199, v221
	v_xor_b32_e32 v220, 16, v226
	v_lshlrev_b32_e32 v220, 2, v220
	ds_bpermute_b32 v47, v220, v46
	v_lshl_add_u32 v199, v146, 2, s38
	ds_read_b32 v159, v199 offset:640
	s_waitcnt lgkmcnt(0)
; __device__ __forceinline__ u32x4 pack8(f32x4 a, f32x4 b) { u32x4 w; w.x = cvt_pk_bf16(a[0], a[1]); w.y = cvt_pk_bf16(a[2], a[3]); w.z = cvt_pk_bf16(b[0], b[1]); w.w = cvt_pk_bf16(b[2], b[3]); return w; }
; __device__ __forceinline__ void unpack8(u32x4 w, f32x4& a, f32x4& b) { a = (f32x4){bflo(w.x), bfhi(w.x), bflo(w.y), bfhi(w.y)}; b = (f32x4){bflo(w.z), bfhi(w.z), bflo(w.w), bfhi(w.w)}; }
; __device__ __forceinline__ float sigmoidf_(float x) { return __builtin_amdgcn_rcpf(1.f + __builtin_amdgcn_exp2f(-1.4426950408889634f * x)); }
; __device__ __forceinline__ float xhalf_sum(float v) { const auto r_ = __builtin_amdgcn_permlane32_swap(__float_as_uint(v), __float_as_uint(v), false, false); return __uint_as_float(r_[0]) + __uint_as_float(r_[1]); }
; #define EPI_ROWS_END if (m & 1) asm volatile("" ::: "memory"); }
;     __device__ __forceinline__ void operator()(AccRef acc, const Unit& u, int wr, int wc, int fr, int fq) const {
;         const int col0 = u.pn * 256 + wc * 32 + 8 * fq;
;         EPI_ROWS_BEGIN
;             float r = 1.f; if (MODE == 1) r = RSL(u, row);
;             float ss = 0.f;
; #pragma unroll
;             for (int bj = 0; bj < 2; ++bj) {
;                 const size_t off = (size_t)row * 1024 + col0 + bj * 128;
;                 f32x4 a0 = acc[ai][bj][m][0], a1 = acc[ai][bj][m][1];
;                 if (MODE == 1) { f32x4 t0, t1; unpack8(*(const u32x4*)(tp + off), t0, t1);
; #pragma unroll
;                     for (int e = 0; e < 4; ++e) { a0[e] = sigmoidf_(a0[e] * r) * t0[e]; a1[e] = sigmoidf_(a1[e] * r) * t1[e]; } }
;                 const f32x4 n0 = *(const f32x4*)(xold + off) + a0, n1 = *(const f32x4*)(xold + off + 4) + a1;
;                 *(f32x4*)(xf + off) = n0; *(f32x4*)(xf + off + 4) = n1;
;                 if (MODE == 0) *(u32x4*)(xb + off) = pack8(n0, n1);
;                 ss += (n0[0] * n0[0] + n0[1] * n0[1]) + (n0[2] * n0[2] + n0[3] * n0[3]) + (n1[0] * n1[0] + n1[1] * n1[1]) + (n1[2] * n1[2] + n1[3] * n1[3]);
;             }
;             ss += __shfl_xor(ss, 16); ss = xhalf_sum(ss);
;             if (fq == 0) ssq_out[(size_t)row * 16 + u.pn * 4 + wc] = ss;
;         EPI_ROWS_END
	v_mul_f32_e32 v30, v30, v159
	v_mul_f32_e32 v31, v31, v159
	v_mul_f32_e32 v32, v32, v159
	v_mul_f32_e32 v33, v33, v159
	v_mul_f32_e32 v26, v26, v159
	v_mul_f32_e32 v27, v27, v159
	v_mul_f32_e32 v28, v28, v159
	v_mul_f32_e32 v29, v29, v159
	v_mul_f32_e32 v22, v22, v159
	v_mul_f32_e32 v23, v23, v159
	v_mul_f32_e32 v24, v24, v159
	v_mul_f32_e32 v25, v25, v159
	v_mul_f32_e32 v18, v18, v159
	v_mul_f32_e32 v19, v19, v159
	v_mul_f32_e32 v20, v20, v159
	v_mul_f32_e32 v21, v21, v159
	v_mul_f32_e32 v30, 0xbfb8aa3b, v30
	v_mul_f32_e32 v31, 0xbfb8aa3b, v31
	v_mul_f32_e32 v32, 0xbfb8aa3b, v32
	v_mul_f32_e32 v33, 0xbfb8aa3b, v33
	v_mul_f32_e32 v26, 0xbfb8aa3b, v26
	v_mul_f32_e32 v27, 0xbfb8aa3b, v27
	v_mul_f32_e32 v28, 0xbfb8aa3b, v28
	v_mul_f32_e32 v29, 0xbfb8aa3b, v29
	v_mul_f32_e32 v22, 0xbfb8aa3b, v22
	v_mul_f32_e32 v23, 0xbfb8aa3b, v23
	v_mul_f32_e32 v24, 0xbfb8aa3b, v24
	v_mul_f32_e32 v25, 0xbfb8aa3b, v25
	v_mul_f32_e32 v18, 0xbfb8aa3b, v18
	v_mul_f32_e32 v19, 0xbfb8aa3b, v19
	v_mul_f32_e32 v20, 0xbfb8aa3b, v20
	v_mul_f32_e32 v21, 0xbfb8aa3b, v21
	v_exp_f32_e32 v30, v30
	v_exp_f32_e32 v31, v31
	v_exp_f32_e32 v32, v32
	v_exp_f32_e32 v33, v33
	v_exp_f32_e32 v26, v26
	v_exp_f32_e32 v27, v27
	v_exp_f32_e32 v28, v28
	v_exp_f32_e32 v29, v29
	v_exp_f32_e32 v22, v22
	v_exp_f32_e32 v23, v23
	v_exp_f32_e32 v24, v24
	v_exp_f32_e32 v25, v25
	v_exp_f32_e32 v18, v18
	v_exp_f32_e32 v19, v19
	v_exp_f32_e32 v20, v20
	v_exp_f32_e32 v21, v21
	v_add_f32_e32 v30, 1.0, v30
	v_add_f32_e32 v31, 1.0, v31
	v_add_f32_e32 v32, 1.0, v32
	v_add_f32_e32 v33, 1.0, v33
	v_add_f32_e32 v26, 1.0, v26
	v_add_f32_e32 v27, 1.0, v27
	v_add_f32_e32 v28, 1.0, v28
	v_add_f32_e32 v29, 1.0, v29
	v_add_f32_e32 v22, 1.0, v22
	v_add_f32_e32 v23, 1.0, v23
	v_add_f32_e32 v24, 1.0, v24
	v_add_f32_e32 v25, 1.0, v25
	v_add_f32_e32 v18, 1.0, v18
	v_add_f32_e32 v19, 1.0, v19
	v_add_f32_e32 v20, 1.0, v20
	v_add_f32_e32 v21, 1.0, v21
	v_rcp_f32_e32 v30, v30
	v_rcp_f32_e32 v31, v31
	v_rcp_f32_e32 v32, v32
	v_rcp_f32_e32 v33, v33
	v_rcp_f32_e32 v26, v26
	v_rcp_f32_e32 v27, v27
	v_rcp_f32_e32 v28, v28
	v_rcp_f32_e32 v29, v29
	v_rcp_f32_e32 v22, v22
	v_rcp_f32_e32 v23, v23
	v_rcp_f32_e32 v24, v24
	v_rcp_f32_e32 v25, v25
	v_rcp_f32_e32 v18, v18
	v_rcp_f32_e32 v19, v19
	v_rcp_f32_e32 v20, v20
	v_rcp_f32_e32 v21, v21
	s_waitcnt vmcnt(14)
	v_lshlrev_b32_e32 v150, 16, v140
	v_and_b32_e32 v151, 0xffff0000, v140
	v_lshlrev_b32_e32 v152, 16, v141
	v_and_b32_e32 v153, 0xffff0000, v141
	v_lshlrev_b32_e32 v154, 16, v142
	v_and_b32_e32 v155, 0xffff0000, v142
	v_lshlrev_b32_e32 v156, 16, v143
	v_and_b32_e32 v157, 0xffff0000, v143
	v_pk_fma_f32 v[164:165], v[30:31], v[150:151], v[164:165]
	v_pk_fma_f32 v[166:167], v[32:33], v[152:153], v[166:167]
	v_pk_fma_f32 v[168:169], v[26:27], v[154:155], v[168:169]
	v_pk_fma_f32 v[170:171], v[28:29], v[156:157], v[170:171]
	v_lshlrev_b32_e32 v150, 16, v160
	v_and_b32_e32 v151, 0xffff0000, v160
	v_lshlrev_b32_e32 v152, 16, v161
	v_and_b32_e32 v153, 0xffff0000, v161
	v_lshlrev_b32_e32 v154, 16, v162
	v_and_b32_e32 v155, 0xffff0000, v162
	v_lshlrev_b32_e32 v156, 16, v163
	v_and_b32_e32 v157, 0xffff0000, v163
	v_pk_fma_f32 v[172:173], v[22:23], v[150:151], v[172:173]
	v_pk_fma_f32 v[174:175], v[24:25], v[152:153], v[174:175]
	v_pk_fma_f32 v[176:177], v[18:19], v[154:155], v[176:177]
	v_pk_fma_f32 v[178:179], v[20:21], v[156:157], v[178:179]
	v_add_u32_e32 v145, 0xa0000, v144
	global_store_dwordx4 v145, v[164:167], s[8:9]
	global_store_dwordx4 v145, v[168:171], s[8:9] offset:16
	global_store_dwordx4 v145, v[172:175], s[8:9] offset:512
	global_store_dwordx4 v145, v[176:179], s[8:9] offset:528
	v_mul_f32_e32 v220, v165, v165
	v_fmac_f32_e32 v220, v164, v164
	v_mul_f32_e32 v221, v167, v167
	v_fmac_f32_e32 v221, v166, v166
	v_add_f32_e32 v221, v220, v221
	v_mul_f32_e32 v220, v169, v169
	v_fmac_f32_e32 v220, v168, v168
	v_add_f32_e32 v221, v221, v220
	v_mul_f32_e32 v220, v171, v171
	v_fmac_f32_e32 v220, v170, v170
	v_add_f32_e32 v199, v220, v221
	v_mul_f32_e32 v220, v173, v173
	v_fmac_f32_e32 v220, v172, v172
	v_mul_f32_e32 v221, v175, v175
	v_fmac_f32_e32 v221, v174, v174
	v_add_f32_e32 v221, v220, v221
	v_mul_f32_e32 v220, v177, v177
	v_fmac_f32_e32 v220, v176, v176
	v_add_f32_e32 v221, v221, v220
	v_mul_f32_e32 v220, v179, v179
	v_fmac_f32_e32 v220, v178, v178
	v_add_f32_e32 v221, v220, v221
	v_add_f32_e32 v30, v199, v221
	v_xor_b32_e32 v220, 16, v226
	v_lshlrev_b32_e32 v220, 2, v220
	ds_bpermute_b32 v31, v220, v30
	v_lshl_add_u32 v199, v146, 2, s38
	ds_read_b32 v159, v199 offset:704
	s_waitcnt lgkmcnt(0)
; __device__ __forceinline__ u32x4 pack8(f32x4 a, f32x4 b) { u32x4 w; w.x = cvt_pk_bf16(a[0], a[1]); w.y = cvt_pk_bf16(a[2], a[3]); w.z = cvt_pk_bf16(b[0], b[1]); w.w = cvt_pk_bf16(b[2], b[3]); return w; }
; __device__ __forceinline__ void unpack8(u32x4 w, f32x4& a, f32x4& b) { a = (f32x4){bflo(w.x), bfhi(w.x), bflo(w.y), bfhi(w.y)}; b = (f32x4){bflo(w.z), bfhi(w.z), bflo(w.w), bfhi(w.w)}; }
; __device__ __forceinline__ float sigmoidf_(float x) { return __builtin_amdgcn_rcpf(1.f + __builtin_amdgcn_exp2f(-1.4426950408889634f * x)); }
; __device__ __forceinline__ float xhalf_sum(float v) { const auto r_ = __builtin_amdgcn_permlane32_swap(__float_as_uint(v), __float_as_uint(v), false, false); return __uint_as_float(r_[0]) + __uint_as_float(r_[1]); }
; #define EPI_ROWS_END if (m & 1) asm volatile("" ::: "memory"); }
;     __device__ __forceinline__ void operator()(AccRef acc, const Unit& u, int wr, int wc, int fr, int fq) const {
;         const int col0 = u.pn * 256 + wc * 32 + 8 * fq;
;         EPI_ROWS_BEGIN
;             float r = 1.f; if (MODE == 1) r = RSL(u, row);
;             float ss = 0.f;
; #pragma unroll
;             for (int bj = 0; bj < 2; ++bj) {
;                 const size_t off = (size_t)row * 1024 + col0 + bj * 128;
;                 f32x4 a0 = acc[ai][bj][m][0], a1 = acc[ai][bj][m][1];
;                 if (MODE == 1) { f32x4 t0, t1; unpack8(*(const u32x4*)(tp + off), t0, t1);
; #pragma unroll
;                     for (int e = 0; e < 4; ++e) { a0[e] = sigmoidf_(a0[e] * r) * t0[e]; a1[e] = sigmoidf_(a1[e] * r) * t1[e]; } }
;                 const f32x4 n0 = *(const f32x4*)(xold + off) + a0, n1 = *(const f32x4*)(xold + off + 4) + a1;
;                 *(f32x4*)(xf + off) = n0; *(f32x4*)(xf + off + 4) = n1;
;                 if (MODE == 0) *(u32x4*)(xb + off) = pack8(n0, n1);
;                 ss += (n0[0] * n0[0] + n0[1] * n0[1]) + (n0[2] * n0[2] + n0[3] * n0[3]) + (n1[0] * n1[0] + n1[1] * n1[1]) + (n1[2] * n1[2] + n1[3] * n1[3]);
;             }
;             ss += __shfl_xor(ss, 16); ss = xhalf_sum(ss);
;             if (fq == 0) ssq_out[(size_t)row * 16 + u.pn * 4 + wc] = ss;
;         EPI_ROWS_END
	v_mul_f32_e32 v14, v14, v159
	v_mul_f32_e32 v15, v15, v159
	v_mul_f32_e32 v16, v16, v159
	v_mul_f32_e32 v17, v17, v159
	v_mul_f32_e32 v10, v10, v159
	v_mul_f32_e32 v11, v11, v159
	v_mul_f32_e32 v12, v12, v159
	v_mul_f32_e32 v13, v13, v159
	v_mul_f32_e32 v6, v6, v159
	v_mul_f32_e32 v7, v7, v159
	v_mul_f32_e32 v8, v8, v159
	v_mul_f32_e32 v9, v9, v159
	v_mul_f32_e32 v2, v2, v159
	v_mul_f32_e32 v3, v3, v159
	v_mul_f32_e32 v4, v4, v159
	v_mul_f32_e32 v5, v5, v159
	v_mul_f32_e32 v14, 0xbfb8aa3b, v14
	v_mul_f32_e32 v15, 0xbfb8aa3b, v15
	v_mul_f32_e32 v16, 0xbfb8aa3b, v16
	v_mul_f32_e32 v17, 0xbfb8aa3b, v17
	v_mul_f32_e32 v10, 0xbfb8aa3b, v10
	v_mul_f32_e32 v11, 0xbfb8aa3b, v11
	v_mul_f32_e32 v12, 0xbfb8aa3b, v12
	v_mul_f32_e32 v13, 0xbfb8aa3b, v13
	v_mul_f32_e32 v6, 0xbfb8aa3b, v6
	v_mul_f32_e32 v7, 0xbfb8aa3b, v7
	v_mul_f32_e32 v8, 0xbfb8aa3b, v8
	v_mul_f32_e32 v9, 0xbfb8aa3b, v9
	v_mul_f32_e32 v2, 0xbfb8aa3b, v2
	v_mul_f32_e32 v3, 0xbfb8aa3b, v3
	v_mul_f32_e32 v4, 0xbfb8aa3b, v4
	v_mul_f32_e32 v5, 0xbfb8aa3b, v5
	v_exp_f32_e32 v14, v14
	v_exp_f32_e32 v15, v15
	v_exp_f32_e32 v16, v16
	v_exp_f32_e32 v17, v17
	v_exp_f32_e32 v10, v10
	v_exp_f32_e32 v11, v11
	v_exp_f32_e32 v12, v12
	v_exp_f32_e32 v13, v13
	v_exp_f32_e32 v6, v6
	v_exp_f32_e32 v7, v7
	v_exp_f32_e32 v8, v8
	v_exp_f32_e32 v9, v9
	v_exp_f32_e32 v2, v2
	v_exp_f32_e32 v3, v3
	v_exp_f32_e32 v4, v4
	v_exp_f32_e32 v5, v5
	v_add_f32_e32 v14, 1.0, v14
	v_add_f32_e32 v15, 1.0, v15
	v_add_f32_e32 v16, 1.0, v16
	v_add_f32_e32 v17, 1.0, v17
	v_add_f32_e32 v10, 1.0, v10
	v_add_f32_e32 v11, 1.0, v11
	v_add_f32_e32 v12, 1.0, v12
	v_add_f32_e32 v13, 1.0, v13
	v_add_f32_e32 v6, 1.0, v6
	v_add_f32_e32 v7, 1.0, v7
	v_add_f32_e32 v8, 1.0, v8
	v_add_f32_e32 v9, 1.0, v9
	v_add_f32_e32 v2, 1.0, v2
	v_add_f32_e32 v3, 1.0, v3
	v_add_f32_e32 v4, 1.0, v4
	v_add_f32_e32 v5, 1.0, v5
	v_rcp_f32_e32 v14, v14
	v_rcp_f32_e32 v15, v15
	v_rcp_f32_e32 v16, v16
	v_rcp_f32_e32 v17, v17
	v_rcp_f32_e32 v10, v10
	v_rcp_f32_e32 v11, v11
	v_rcp_f32_e32 v12, v12
	v_rcp_f32_e32 v13, v13
	v_rcp_f32_e32 v6, v6
	v_rcp_f32_e32 v7, v7
	v_rcp_f32_e32 v8, v8
	v_rcp_f32_e32 v9, v9
	v_rcp_f32_e32 v2, v2
	v_rcp_f32_e32 v3, v3
	v_rcp_f32_e32 v4, v4
	v_rcp_f32_e32 v5, v5
	s_waitcnt vmcnt(8)
	v_lshlrev_b32_e32 v150, 16, v180
	v_and_b32_e32 v151, 0xffff0000, v180
	v_lshlrev_b32_e32 v152, 16, v181
	v_and_b32_e32 v153, 0xffff0000, v181
	v_lshlrev_b32_e32 v154, 16, v182
	v_and_b32_e32 v155, 0xffff0000, v182
	v_lshlrev_b32_e32 v156, 16, v183
	v_and_b32_e32 v157, 0xffff0000, v183
	v_pk_fma_f32 v[188:189], v[14:15], v[150:151], v[188:189]
	v_pk_fma_f32 v[190:191], v[16:17], v[152:153], v[190:191]
	v_pk_fma_f32 v[192:193], v[10:11], v[154:155], v[192:193]
	v_pk_fma_f32 v[194:195], v[12:13], v[156:157], v[194:195]
	v_lshlrev_b32_e32 v150, 16, v184
	v_and_b32_e32 v151, 0xffff0000, v184
	v_lshlrev_b32_e32 v152, 16, v185
	v_and_b32_e32 v153, 0xffff0000, v185
	v_lshlrev_b32_e32 v154, 16, v186
	v_and_b32_e32 v155, 0xffff0000, v186
	v_lshlrev_b32_e32 v156, 16, v187
	v_and_b32_e32 v157, 0xffff0000, v187
	v_pk_fma_f32 v[200:201], v[6:7], v[150:151], v[200:201]
	v_pk_fma_f32 v[202:203], v[8:9], v[152:153], v[202:203]
	v_pk_fma_f32 v[204:205], v[2:3], v[154:155], v[204:205]
	v_pk_fma_f32 v[206:207], v[4:5], v[156:157], v[206:207]
	v_add_u32_e32 v145, 0xb0000, v144
	global_store_dwordx4 v145, v[188:191], s[8:9]
	global_store_dwordx4 v145, v[192:195], s[8:9] offset:16
	global_store_dwordx4 v145, v[200:203], s[8:9] offset:512
	global_store_dwordx4 v145, v[204:207], s[8:9] offset:528
	v_mul_f32_e32 v220, v189, v189
	v_fmac_f32_e32 v220, v188, v188
	v_mul_f32_e32 v221, v191, v191
	v_fmac_f32_e32 v221, v190, v190
	v_add_f32_e32 v221, v220, v221
	v_mul_f32_e32 v220, v193, v193
	v_fmac_f32_e32 v220, v192, v192
	v_add_f32_e32 v221, v221, v220
	v_mul_f32_e32 v220, v195, v195
	v_fmac_f32_e32 v220, v194, v194
	v_add_f32_e32 v199, v220, v221
	v_mul_f32_e32 v220, v201, v201
	v_fmac_f32_e32 v220, v200, v200
	v_mul_f32_e32 v221, v203, v203
	v_fmac_f32_e32 v221, v202, v202
	v_add_f32_e32 v221, v220, v221
	v_mul_f32_e32 v220, v205, v205
	v_fmac_f32_e32 v220, v204, v204
	v_add_f32_e32 v221, v221, v220
	v_mul_f32_e32 v220, v207, v207
	v_fmac_f32_e32 v220, v206, v206
	v_add_f32_e32 v221, v220, v221
	v_add_f32_e32 v14, v199, v221
	v_xor_b32_e32 v220, 16, v226
	v_lshlrev_b32_e32 v220, 2, v220
	ds_bpermute_b32 v15, v220, v14
	s_waitcnt lgkmcnt(0)
	v_add_f32_e32 v122, v122, v123
	v_add_f32_e32 v110, v110, v111
	v_add_f32_e32 v94, v94, v95
	v_add_f32_e32 v78, v78, v79
	v_add_f32_e32 v62, v62, v63
	v_add_f32_e32 v46, v46, v47
	v_add_f32_e32 v30, v30, v31
	v_add_f32_e32 v14, v14, v15
	v_mov_b32_e32 v123, v122
	v_mov_b32_e32 v111, v110
	v_mov_b32_e32 v95, v94
	v_mov_b32_e32 v79, v78
	v_mov_b32_e32 v63, v62
	v_mov_b32_e32 v47, v46
	v_mov_b32_e32 v31, v30
	v_mov_b32_e32 v15, v14
	s_nop 1
	v_permlane32_swap_b32_e32 v122, v123
	v_permlane32_swap_b32_e32 v110, v111
	v_permlane32_swap_b32_e32 v94, v95
	v_permlane32_swap_b32_e32 v78, v79
	v_permlane32_swap_b32_e32 v62, v63
	v_permlane32_swap_b32_e32 v46, v47
	v_permlane32_swap_b32_e32 v30, v31
	v_permlane32_swap_b32_e32 v14, v15
	v_add_f32_e32 v122, v122, v123
	v_add_f32_e32 v110, v110, v111
	v_add_f32_e32 v94, v94, v95
	v_add_f32_e32 v78, v78, v79
	v_add_f32_e32 v62, v62, v63
	v_add_f32_e32 v46, v46, v47
	v_add_f32_e32 v30, v30, v31
	v_add_f32_e32 v14, v14, v15
	s_lshl_b32 s64, s31, 14
	s_lshl_b32 s65, s60, 4
	s_add_u32 s64, s64, s65
	s_lshl_b32 s65, s54, 2
	s_add_u32 s64, s64, s65
	v_lshl_add_u32 v198, v146, 6, s64
	s_and_saveexec_b64 s[28:29], s[42:43]
	global_store_dword v198, v122, s[20:21]
	v_add_u32_e32 v145, 0x400, v198
	global_store_dword v145, v110, s[20:21]
	v_add_u32_e32 v145, 0x800, v198
	global_store_dword v145, v94, s[20:21]
	v_add_u32_e32 v145, 0xc00, v198
	global_store_dword v145, v78, s[20:21]
	v_add_u32_e32 v145, 0x2000, v198
	global_store_dword v145, v62, s[20:21]
	v_add_u32_e32 v145, 0x2400, v198
	global_store_dword v145, v46, s[20:21]
	v_add_u32_e32 v145, 0x2800, v198
	global_store_dword v145, v30, s[20:21]
	v_add_u32_e32 v145, 0x2c00, v198
	global_store_dword v145, v14, s[20:21]
	s_or_b64 exec, exec, s[28:29]
	s_and_b64 vcc, exec, s[44:45]
	s_mov_b64 s[28:29], -1
	s_cbranch_vccnz .LBB0_1760
	s_andn2_b64 vcc, exec, s[18:19]
	s_cbranch_vccnz .LBB0_1759
	s_barrier
	s_branch .LBB0_1759
